# attention K tile image swizzled with row&15 (conflict-free ds_read_b128) on top of v17
# speedup vs baseline: 1.0083x; 1.0010x over previous
.LBB0_1674:
	s_cmp_gt_i32 s2, 31
	s_mov_b64 s[4:5], -1
	s_cbranch_scc0 .LBB0_2020
	s_getreg_b32 s3, hwreg(HW_REG_HW_ID, 0, 6)
	s_lshl_b32 s3, s3, 2
	s_add_i32 s3, s3, 0
	s_add_i32 s3, s3, 0x24200
	v_mov_b32_e32 v0, s3
	ds_read_b32 v0, v0
	v_mbcnt_lo_u32_b32 v2, -1, 0
	v_mbcnt_hi_u32_b32 v2, -1, v2
	s_and_b32 s20, s2, 15
	s_and_b32 s12, s2, 3
	v_readlane_b32 s6, v254, 47
	s_waitcnt lgkmcnt(0)
	v_readfirstlane_b32 s3, v0
	s_mul_i32 s13, s12, 0x420
	v_mov_b32_e32 v99, 0
	v_lshl_add_u32 v189, s3, 6, v2
	v_mov_b32_e32 v102, 0
	v_readfirstlane_b32 s3, v189
	v_bfe_u32 v139, v189, 4, 2
	s_ashr_i32 s3, s3, 6
	v_bfe_u32 v2, v189, 2, 2
	v_lshrrev_b32_e32 v3, 1, v189
	v_bitop3_b32 v4, v139, v189, 15 bitop3:0x78
	v_and_b32_e32 v155, 63, v189
	v_and_or_b32 v2, v3, 8, v2
	s_lshl_b32 s5, s3, 11
	v_lshlrev_b32_e32 v3, 8, v139
	v_lshlrev_b32_e32 v4, 4, v4
	s_lshl_b32 s59, s3, 7
	v_or3_b32 v172, v4, v3, s5
	v_or_b32_e32 v3, s59, v155
	v_lshlrev_b32_e32 v151, 3, v155
	v_ashrrev_i32_e32 v3, 4, v3
	v_and_b32_e32 v98, 24, v151
	v_and_b32_e32 v194, 32, v189
	v_and_b32_e32 v5, 0xfffff0, v3
	v_lshrrev_b32_e32 v3, 1, v3
	s_lshl_b32 s4, s3, 1
	v_or_b32_e32 v4, v98, v194
	v_and_b32_e32 v3, 4, v3
	v_or3_b32 v3, v5, v3, v2
	v_lshlrev_b32_e32 v4, 1, v4
	s_or_b32 s4, s4, 1
	v_and_b32_e32 v0, 15, v189
	v_lshl_or_b32 v174, v3, 8, v4
	v_lshl_or_b32 v3, s4, 2, v139
	v_lshlrev_b32_e32 v4, 8, v3
	v_bitop3_b32 v0, v3, v0, 7 bitop3:0x6c
	v_lshl_or_b32 v176, v0, 4, v4
	v_mov_b32_e32 v66, s3
	v_and_b32_e32 v66, 1, v66
	v_lshlrev_b32_e32 v66, 7, v66
	v_xor_b32_e32 v172, v66, v172
	v_xor_b32_e32 v176, v66, v176
	v_lshl_or_b32 v0, s4, 6, v155
	s_movk_i32 s4, 0x60
	v_ashrrev_i32_e32 v3, 4, v0
	v_and_or_b32 v0, v0, s4, v98
	s_lshl_b32 s4, s20, 15
	s_add_u32 s36, s6, s4
	v_readlane_b32 s6, v254, 48
	s_addc_u32 s37, s6, 0
	v_readlane_b32 s6, v254, 49
	s_add_u32 s38, s6, s4
	v_readlane_b32 s4, v254, 50
	s_addc_u32 s39, s4, 0
	s_add_i32 s47, s5, 0
	v_and_b32_e32 v4, 0xfffff0, v3
	v_lshrrev_b32_e32 v3, 1, v3
	s_add_i32 m0, s47, 0x8000
	v_and_b32_e32 v3, 4, v3
	global_load_lds_dwordx4 v172, s[36:37]
	s_add_i32 m0, s47, 0x8400
	v_or3_b32 v2, v4, v3, v2
	v_lshlrev_b32_e32 v0, 1, v0
	global_load_lds_dwordx4 v176, s[36:37]
	s_mov_b32 m0, s47
	v_lshl_or_b32 v178, v2, 8, v0
	global_load_lds_dwordx4 v174, s[38:39]
	s_add_i32 m0, s47, 0x400
	s_movk_i32 s4, 0x420
	global_load_lds_dwordx4 v178, s[38:39]
	v_cmp_gt_i32_e64 s[4:5], s4, v189
	s_and_saveexec_b64 s[6:7], s[4:5]
	s_cbranch_execz .LBB0_1677
	v_add_u32_e32 v2, s13, v189
	v_readlane_b32 s8, v253, 62
	v_ashrrev_i32_e32 v3, 31, v2
	v_readlane_b32 s9, v253, 63
	s_nop 1
	v_lshl_add_u64 v[2:3], v[2:3], 2, s[8:9]
	global_load_dword v102, v[2:3], off

.LBB0_1697:
	s_or_b64 exec, exec, s[4:5]
	v_max_f32_e64 v0, |v125|, |v125|
	v_max_f32_e64 v99, |v124|, |v124|
	v_max_f32_e32 v0, v99, v0
	ds_swizzle_b32 v99, v0 offset:swizzle(SWAP,1)
	v_max3_f32 v107, v119, v120, v121
	ds_swizzle_b32 v108, v107 offset:swizzle(SWAP,1)
	v_lshlrev_b32_e32 v103, 1, v155
	v_lshlrev_b32_e32 v102, 4, v155
	s_waitcnt lgkmcnt(1)
	v_max_f32_e32 v99, v99, v99
	v_max_f32_e32 v0, v0, v99
	ds_swizzle_b32 v99, v0 offset:swizzle(SWAP,2)
	s_waitcnt lgkmcnt(1)
	v_max_f32_e32 v108, v108, v108
	v_max_f32_e32 v107, v107, v108
	ds_swizzle_b32 v108, v107 offset:swizzle(SWAP,2)
	v_and_b32_e32 v104, 0x100, v151
	s_waitcnt lgkmcnt(1)
	v_max_f32_e32 v99, v99, v99
	v_max_f32_e32 v0, v0, v99
	ds_swizzle_b32 v99, v0 offset:swizzle(SWAP,4)
	v_and_b32_e32 v103, 32, v103
	v_and_b32_e32 v102, 0xc0, v102
	v_add3_u32 v103, v104, 0, v103
	v_add3_u32 v181, v103, v102, v98
	s_waitcnt lgkmcnt(1)
	v_max_f32_e32 v98, v108, v108
	v_max_f32_e64 v103, |v112|, |v112|
	v_max_f32_e64 v104, |v111|, |v111|
	v_max_f32_e32 v98, v107, v98
	v_max_f32_e32 v103, v104, v103
	s_waitcnt lgkmcnt(0)
	v_max_f32_e32 v99, v99, v99
	ds_swizzle_b32 v102, v98 offset:swizzle(SWAP,4)
	ds_swizzle_b32 v104, v103 offset:swizzle(SWAP,1)
	v_max_f32_e32 v0, v0, v99
	ds_swizzle_b32 v99, v0 offset:swizzle(SWAP,8)
	v_max_f32_e64 v101, |v101|, |v101|
	s_waitcnt lgkmcnt(2)
	v_max_f32_e32 v102, v102, v102
	s_waitcnt lgkmcnt(1)
	v_max_f32_e32 v104, v104, v104
	v_max_f32_e32 v98, v98, v102
	v_max_f32_e32 v103, v103, v104
	s_waitcnt lgkmcnt(0)
	v_max_f32_e32 v99, v99, v99
	ds_swizzle_b32 v102, v98 offset:swizzle(SWAP,8)
	ds_swizzle_b32 v104, v103 offset:swizzle(SWAP,2)
	v_max_f32_e32 v0, v0, v99
	ds_swizzle_b32 v99, v0 offset:swizzle(SWAP,16)
	v_max_f32_e64 v100, |v100|, |v100|
	s_waitcnt lgkmcnt(2)
	v_max_f32_e32 v102, v102, v102
	s_waitcnt lgkmcnt(1)
	v_max_f32_e32 v104, v104, v104
	v_max_f32_e32 v98, v98, v102
	v_max_f32_e32 v103, v103, v104
	s_waitcnt lgkmcnt(0)
	v_max_f32_e32 v99, v99, v99
	ds_swizzle_b32 v102, v98 offset:swizzle(SWAP,16)
	ds_swizzle_b32 v104, v103 offset:swizzle(SWAP,4)
	v_max_f32_e32 v0, v0, v99
	v_mov_b32_e32 v99, v0
	s_nop 1
	v_permlane32_swap_b32_e32 v0, v99
	v_max_f32_e32 v99, v99, v99
	v_max_f32_e32 v0, v0, v0
	v_max_f32_e32 v0, v0, v99
	s_waitcnt lgkmcnt(1)
	v_max_f32_e32 v99, v102, v102
	s_waitcnt lgkmcnt(0)
	v_max_f32_e32 v102, v104, v104
	v_max_f32_e32 v102, v103, v102
	ds_swizzle_b32 v103, v102 offset:swizzle(SWAP,8)
	v_max_f32_e32 v98, v98, v99
	v_mov_b32_e32 v99, v98
	s_nop 1
	v_permlane32_swap_b32_e32 v98, v99
	v_max_f32_e32 v99, v99, v99
	v_max_f32_e32 v98, v98, v98
	v_max_f32_e32 v190, v98, v99
	s_waitcnt lgkmcnt(0)
	v_max_f32_e32 v98, v103, v103
	v_max_f32_e32 v98, v102, v98
	v_max_f32_e64 v102, |v106|, |v106|
	v_max_f32_e64 v103, |v105|, |v105|
	v_max_f32_e32 v102, v103, v102
	ds_swizzle_b32 v99, v98 offset:swizzle(SWAP,16)
	ds_swizzle_b32 v103, v102 offset:swizzle(SWAP,1)
	v_max_f32_e32 v100, v100, v101
	ds_swizzle_b32 v101, v100 offset:swizzle(SWAP,1)
	v_mul_f32_e32 v191, 0x4182b55c, v0
	s_waitcnt lgkmcnt(2)
	v_max_f32_e32 v0, v99, v99
	s_waitcnt lgkmcnt(1)
	v_max_f32_e32 v99, v103, v103
	v_max_f32_e32 v99, v102, v99
	s_waitcnt lgkmcnt(0)
	v_max_f32_e32 v101, v101, v101
	ds_swizzle_b32 v102, v99 offset:swizzle(SWAP,2)
	v_max_f32_e32 v100, v100, v101
	ds_swizzle_b32 v101, v100 offset:swizzle(SWAP,2)
	v_max_f32_e32 v0, v98, v0
	v_mov_b32_e32 v98, v0
	s_waitcnt lgkmcnt(1)
	v_max_f32_e32 v102, v102, v102
	v_max_f32_e32 v99, v99, v102
	s_waitcnt lgkmcnt(0)
	v_max_f32_e32 v101, v101, v101
	ds_swizzle_b32 v102, v99 offset:swizzle(SWAP,4)
	v_max_f32_e32 v100, v100, v101
	ds_swizzle_b32 v101, v100 offset:swizzle(SWAP,4)
	v_permlane32_swap_b32_e32 v0, v98
	s_waitcnt lgkmcnt(1)
	v_max_f32_e32 v102, v102, v102
	v_max_f32_e32 v99, v99, v102
	s_waitcnt lgkmcnt(0)
	v_max_f32_e32 v101, v101, v101
	ds_swizzle_b32 v102, v99 offset:swizzle(SWAP,8)
	v_max_f32_e32 v100, v100, v101
	ds_swizzle_b32 v101, v100 offset:swizzle(SWAP,8)
	v_max_f32_e32 v98, v98, v98
	v_max_f32_e32 v0, v0, v0
	s_waitcnt lgkmcnt(1)
	v_max_f32_e32 v102, v102, v102
	v_max_f32_e32 v99, v99, v102
	v_max_f32_e32 v0, v0, v98
	s_waitcnt lgkmcnt(0)
	v_max_f32_e32 v98, v101, v101
	ds_swizzle_b32 v102, v99 offset:swizzle(SWAP,16)
	v_max_f32_e32 v98, v100, v98
	ds_swizzle_b32 v100, v98 offset:swizzle(SWAP,16)
	v_fma_f32 v0, v191, v0, v190
	v_add_f32_e32 v195, 0x3d4ccccd, v0
	s_waitcnt lgkmcnt(1)
	v_max_f32_e32 v0, v102, v102
	v_max_f32_e32 v0, v99, v0
	s_waitcnt lgkmcnt(0)
	v_max_f32_e32 v99, v100, v100
	v_max_f32_e32 v192, v98, v99
	v_lshlrev_b32_e32 v98, 16, v94
	v_and_b32_e32 v94, 0xffff0000, v94
	v_mul_f32_e32 v102, v94, v94
	v_lshlrev_b32_e32 v99, 16, v95
	v_fmac_f32_e32 v102, v98, v98
	v_and_b32_e32 v95, 0xffff0000, v95
	v_fmac_f32_e32 v102, v99, v99
	v_lshlrev_b32_e32 v100, 16, v96
	v_fmac_f32_e32 v102, v95, v95
	v_and_b32_e32 v96, 0xffff0000, v96
	v_fmac_f32_e32 v102, v100, v100
	v_lshlrev_b32_e32 v101, 16, v97
	v_fmac_f32_e32 v102, v96, v96
	v_and_b32_e32 v97, 0xffff0000, v97
	v_fmac_f32_e32 v102, v101, v101
	v_fmac_f32_e32 v102, v97, v97
	v_lshlrev_b32_e32 v103, 16, v90
	v_and_b32_e32 v90, 0xffff0000, v90
	v_fmac_f32_e32 v102, v103, v103
	v_lshlrev_b32_e32 v104, 16, v91
	v_fmac_f32_e32 v102, v90, v90
	v_and_b32_e32 v91, 0xffff0000, v91
	v_fmac_f32_e32 v102, v104, v104
	v_lshlrev_b32_e32 v105, 16, v92
	v_fmac_f32_e32 v102, v91, v91
	v_and_b32_e32 v92, 0xffff0000, v92
	v_fmac_f32_e32 v102, v105, v105
	v_lshlrev_b32_e32 v106, 16, v93
	v_fmac_f32_e32 v102, v92, v92
	v_and_b32_e32 v93, 0xffff0000, v93
	v_fmac_f32_e32 v102, v106, v106
	v_fmac_f32_e32 v102, v93, v93
	v_lshlrev_b32_e32 v107, 16, v86
	v_and_b32_e32 v86, 0xffff0000, v86
	v_fmac_f32_e32 v102, v107, v107
	v_lshlrev_b32_e32 v108, 16, v87
	v_fmac_f32_e32 v102, v86, v86
	v_and_b32_e32 v87, 0xffff0000, v87
	v_fmac_f32_e32 v102, v108, v108
	v_lshlrev_b32_e32 v109, 16, v88
	v_fmac_f32_e32 v102, v87, v87
	v_and_b32_e32 v88, 0xffff0000, v88
	v_fmac_f32_e32 v102, v109, v109
	v_lshlrev_b32_e32 v110, 16, v89
	v_fmac_f32_e32 v102, v88, v88
	v_and_b32_e32 v89, 0xffff0000, v89
	v_fmac_f32_e32 v102, v110, v110
	v_fmac_f32_e32 v102, v89, v89
	v_lshlrev_b32_e32 v111, 16, v82
	v_and_b32_e32 v82, 0xffff0000, v82
	v_fmac_f32_e32 v102, v111, v111
	v_lshlrev_b32_e32 v112, 16, v83
	v_fmac_f32_e32 v102, v82, v82
	v_and_b32_e32 v83, 0xffff0000, v83
	v_fmac_f32_e32 v102, v112, v112
	v_lshlrev_b32_e32 v113, 16, v84
	v_fmac_f32_e32 v102, v83, v83
	v_and_b32_e32 v84, 0xffff0000, v84
	v_fmac_f32_e32 v102, v113, v113
	v_lshlrev_b32_e32 v114, 16, v85
	v_fmac_f32_e32 v102, v84, v84
	v_and_b32_e32 v85, 0xffff0000, v85
	v_fmac_f32_e32 v102, v114, v114
	v_fmac_f32_e32 v102, v85, v85
	v_lshlrev_b32_e32 v115, 16, v78
	v_and_b32_e32 v78, 0xffff0000, v78
	v_fmac_f32_e32 v102, v115, v115
	v_lshlrev_b32_e32 v116, 16, v79
	v_fmac_f32_e32 v102, v78, v78
	v_and_b32_e32 v79, 0xffff0000, v79
	v_fmac_f32_e32 v102, v116, v116
	v_lshlrev_b32_e32 v117, 16, v80
	v_fmac_f32_e32 v102, v79, v79
	v_and_b32_e32 v80, 0xffff0000, v80
	v_fmac_f32_e32 v102, v117, v117
	v_lshlrev_b32_e32 v118, 16, v81
	v_fmac_f32_e32 v102, v80, v80
	v_and_b32_e32 v81, 0xffff0000, v81
	v_fmac_f32_e32 v102, v118, v118
	v_fmac_f32_e32 v102, v81, v81
	v_lshlrev_b32_e32 v119, 16, v74
	v_and_b32_e32 v74, 0xffff0000, v74
	v_fmac_f32_e32 v102, v119, v119
	v_lshlrev_b32_e32 v120, 16, v75
	v_fmac_f32_e32 v102, v74, v74
	v_and_b32_e32 v75, 0xffff0000, v75
	v_fmac_f32_e32 v102, v120, v120
	v_lshlrev_b32_e32 v121, 16, v76
	v_fmac_f32_e32 v102, v75, v75
	v_and_b32_e32 v76, 0xffff0000, v76
	v_fmac_f32_e32 v102, v121, v121
	v_lshlrev_b32_e32 v122, 16, v77
	v_fmac_f32_e32 v102, v76, v76
	v_and_b32_e32 v77, 0xffff0000, v77
	v_fmac_f32_e32 v102, v122, v122
	v_fmac_f32_e32 v102, v77, v77
	v_lshlrev_b32_e32 v123, 16, v70
	v_and_b32_e32 v70, 0xffff0000, v70
	v_fmac_f32_e32 v102, v123, v123
	v_lshlrev_b32_e32 v124, 16, v71
	v_fmac_f32_e32 v102, v70, v70
	v_and_b32_e32 v71, 0xffff0000, v71
	v_fmac_f32_e32 v102, v124, v124
	v_lshlrev_b32_e32 v125, 16, v72
	v_fmac_f32_e32 v102, v71, v71
	v_and_b32_e32 v72, 0xffff0000, v72
	v_fmac_f32_e32 v102, v125, v125
	v_lshlrev_b32_e32 v126, 16, v73
	v_fmac_f32_e32 v102, v72, v72
	v_and_b32_e32 v73, 0xffff0000, v73
	v_fmac_f32_e32 v102, v126, v126
	v_fmac_f32_e32 v102, v73, v73
	v_lshlrev_b32_e32 v127, 16, v66
	v_and_b32_e32 v66, 0xffff0000, v66
	v_fmac_f32_e32 v102, v127, v127
	v_lshlrev_b32_e32 v159, 16, v67
	v_fmac_f32_e32 v102, v66, v66
	v_and_b32_e32 v67, 0xffff0000, v67
	v_fmac_f32_e32 v102, v159, v159
	v_lshlrev_b32_e32 v164, 16, v68
	v_fmac_f32_e32 v102, v67, v67
	v_and_b32_e32 v68, 0xffff0000, v68
	v_fmac_f32_e32 v102, v164, v164
	v_lshlrev_b32_e32 v165, 16, v69
	v_fmac_f32_e32 v102, v68, v68
	v_and_b32_e32 v69, 0xffff0000, v69
	v_fmac_f32_e32 v102, v165, v165
	v_fmac_f32_e32 v102, v69, v69
	v_mov_b32_e32 v166, v102
	s_nop 1
	v_permlane32_swap_b32_e32 v102, v166
	v_add_f32_e32 v102, v102, v166
	v_fmamk_f32 v102, v102, 0x3c000000, v163
	v_rsq_f32_e32 v102, v102
	s_cmpk_gt_u32 s55, 0x1ff
	s_cselect_b64 s[8:9], -1, 0
	s_cmpk_lt_u32 s55, 0x200
	v_mul_f32_e32 v102, 0x3db504f3, v102
	v_mul_f32_e32 v166, 0x3fb8aa3b, v102
	v_mul_f32_e32 v94, v166, v94
	v_mul_f32_e32 v63, v63, v94
	v_mul_f32_e32 v94, v166, v96
	v_mul_f32_e32 v98, v166, v98
	v_mul_f32_e32 v59, v59, v94
	v_mul_f32_e32 v94, v166, v99
	v_mul_f32_e32 v62, v62, v98
	v_mul_f32_e32 v98, v166, v100
	v_mul_f32_e32 v64, v64, v94
	v_mul_f32_e32 v94, v166, v101
	v_mul_f32_e32 v58, v58, v98
	v_mul_f32_e32 v60, v60, v94
	v_mul_f32_e32 v94, v166, v95
	v_mul_f32_e32 v65, v65, v94
	v_cvt_pk_bf16_f32 v98, v62, v63
	v_cvt_pk_bf16_f32 v99, v64, v65
	v_cvt_pk_bf16_f32 v100, v58, v59
	v_mul_f32_e32 v58, v166, v103
	v_mul_f32_e32 v54, v54, v58
	v_mul_f32_e32 v58, v166, v105
	v_mul_f32_e32 v50, v50, v58
	v_mul_f32_e32 v58, v166, v90
	v_mul_f32_e32 v55, v55, v58
	v_mul_f32_e32 v58, v166, v92
	v_mul_f32_e32 v51, v51, v58
	v_mul_f32_e32 v58, v166, v104
	v_mul_f32_e32 v56, v56, v58
	v_mul_f32_e32 v58, v166, v106
	v_mul_f32_e32 v94, v166, v97
	v_mul_f32_e32 v52, v52, v58
	v_mul_f32_e32 v58, v166, v91
	v_mul_f32_e32 v61, v61, v94
	v_cvt_pk_bf16_f32 v101, v60, v61
	v_mul_f32_e32 v57, v57, v58
	v_cvt_pk_bf16_f32 v102, v54, v55
	v_cvt_pk_bf16_f32 v103, v56, v57
	v_cvt_pk_bf16_f32 v104, v50, v51
	v_mul_f32_e32 v50, v166, v107
	v_mul_f32_e32 v46, v46, v50
	v_mul_f32_e32 v50, v166, v109
	v_mul_f32_e32 v42, v42, v50
	v_mul_f32_e32 v50, v166, v86
	v_mul_f32_e32 v47, v47, v50
	v_mul_f32_e32 v50, v166, v88
	v_mul_f32_e32 v43, v43, v50
	v_mul_f32_e32 v50, v166, v108
	v_mul_f32_e32 v48, v48, v50
	v_mul_f32_e32 v50, v166, v110
	v_mul_f32_e32 v58, v166, v93
	v_mul_f32_e32 v44, v44, v50
	v_mul_f32_e32 v50, v166, v87
	v_mul_f32_e32 v53, v53, v58
	v_cvt_pk_bf16_f32 v105, v52, v53
	v_mul_f32_e32 v49, v49, v50
	v_cvt_pk_bf16_f32 v106, v46, v47
	v_cvt_pk_bf16_f32 v107, v48, v49
	v_cvt_pk_bf16_f32 v108, v42, v43
	v_mul_f32_e32 v42, v166, v111
	v_mul_f32_e32 v38, v38, v42
	v_mul_f32_e32 v42, v166, v113
	v_mul_f32_e32 v34, v34, v42
	v_mul_f32_e32 v42, v166, v82
	v_mul_f32_e32 v39, v39, v42
	v_mul_f32_e32 v42, v166, v84
	v_mul_f32_e32 v35, v35, v42
	v_mul_f32_e32 v42, v166, v112
	v_mul_f32_e32 v40, v40, v42
	v_mul_f32_e32 v42, v166, v114
	v_mul_f32_e32 v50, v166, v89
	v_mul_f32_e32 v36, v36, v42
	v_mul_f32_e32 v42, v166, v83
	v_mul_f32_e32 v45, v45, v50
	v_cvt_pk_bf16_f32 v109, v44, v45
	v_mul_f32_e32 v41, v41, v42
	v_cvt_pk_bf16_f32 v110, v38, v39
	v_cvt_pk_bf16_f32 v111, v40, v41
	v_cvt_pk_bf16_f32 v112, v34, v35
	v_mul_f32_e32 v34, v166, v115
	v_mul_f32_e32 v30, v30, v34
	v_mul_f32_e32 v34, v166, v117
	v_mul_f32_e32 v26, v26, v34
	v_mul_f32_e32 v34, v166, v78
	v_mul_f32_e32 v31, v31, v34
	v_mul_f32_e32 v34, v166, v80
	v_mul_f32_e32 v27, v27, v34
	v_mul_f32_e32 v34, v166, v116
	v_mul_f32_e32 v32, v32, v34
	v_mul_f32_e32 v34, v166, v118
	v_mul_f32_e32 v42, v166, v85
	v_mul_f32_e32 v28, v28, v34
	v_mul_f32_e32 v34, v166, v79
	v_mul_f32_e32 v37, v37, v42
	v_cvt_pk_bf16_f32 v113, v36, v37
	v_mul_f32_e32 v33, v33, v34
	v_cvt_pk_bf16_f32 v114, v30, v31
	v_cvt_pk_bf16_f32 v115, v32, v33
	v_cvt_pk_bf16_f32 v116, v26, v27
	v_mul_f32_e32 v26, v166, v119
	v_mul_f32_e32 v22, v22, v26
	v_mul_f32_e32 v26, v166, v121
	v_mul_f32_e32 v18, v18, v26
	v_mul_f32_e32 v26, v166, v74
	v_mul_f32_e32 v23, v23, v26
	v_mul_f32_e32 v26, v166, v76
	v_mul_f32_e32 v19, v19, v26
	v_mul_f32_e32 v26, v166, v120
	v_mul_f32_e32 v24, v24, v26
	v_mul_f32_e32 v26, v166, v122
	v_mul_f32_e32 v34, v166, v81
	v_mul_f32_e32 v20, v20, v26
	v_mul_f32_e32 v26, v166, v75
	v_mul_f32_e32 v29, v29, v34
	v_cvt_pk_bf16_f32 v117, v28, v29
	v_mul_f32_e32 v25, v25, v26
	v_cvt_pk_bf16_f32 v118, v22, v23
	v_cvt_pk_bf16_f32 v119, v24, v25
	v_cvt_pk_bf16_f32 v120, v18, v19
	v_mul_f32_e32 v18, v166, v123
	v_mul_f32_e32 v14, v14, v18
	v_mul_f32_e32 v18, v166, v125
	v_mul_f32_e32 v10, v10, v18
	v_mul_f32_e32 v18, v166, v70
	v_mul_f32_e32 v15, v15, v18
	v_mul_f32_e32 v18, v166, v72
	v_mul_f32_e32 v11, v11, v18
	v_mul_f32_e32 v18, v166, v124
	v_mul_f32_e32 v16, v16, v18
	v_mul_f32_e32 v18, v166, v126
	v_mul_f32_e32 v26, v166, v77
	v_mul_f32_e32 v12, v12, v18
	v_mul_f32_e32 v18, v166, v71
	v_mul_f32_e32 v21, v21, v26
	v_cvt_pk_bf16_f32 v121, v20, v21
	v_mul_f32_e32 v17, v17, v18
	v_cvt_pk_bf16_f32 v122, v14, v15
	v_cvt_pk_bf16_f32 v123, v16, v17
	v_cvt_pk_bf16_f32 v124, v10, v11
	v_mul_f32_e32 v10, v166, v127
	v_mul_f32_e32 v6, v6, v10
	v_mul_f32_e32 v10, v166, v164
	v_mul_f32_e32 v2, v2, v10
	v_mul_f32_e32 v10, v166, v66
	v_mul_f32_e32 v7, v7, v10
	v_mul_f32_e32 v10, v166, v68
	v_mul_f32_e32 v3, v3, v10
	v_mul_f32_e32 v10, v166, v159
	v_mul_f32_e32 v18, v166, v73
	v_mul_f32_e32 v8, v8, v10
	v_mul_f32_e32 v10, v166, v165
	v_add_f32_e32 v11, 0, v132
	v_mul_f32_e32 v13, v13, v18
	v_cvt_pk_bf16_f32 v125, v12, v13
	v_mul_f32_e32 v4, v4, v10
	v_mul_f32_e32 v10, v166, v67
	v_add_f32_e32 v11, v11, v136
	v_cvt_pk_bf16_f32 v126, v6, v7
	v_add_f32_e32 v7, 0, v133
	v_mul_f32_e32 v9, v9, v10
	v_add_f32_e32 v11, v11, v140
	v_cvt_pk_bf16_f32 v127, v8, v9
	v_add_f32_e32 v7, v7, v137
	v_add_f32_e32 v8, 0, v134
	v_add_f32_e32 v11, v11, v144
	v_add_f32_e32 v7, v7, v141
	v_add_f32_e32 v8, v8, v138
	v_add_f32_e32 v11, v11, v148
	v_add_f32_e32 v7, v7, v145
	v_add_f32_e32 v8, v8, v142
	v_add_f32_e32 v11, v11, v152
	v_add_f32_e32 v7, v7, v149
	v_add_f32_e32 v8, v8, v146
	v_add_f32_e32 v11, v11, v156
	v_add_f32_e32 v7, v7, v153
	v_add_f32_e32 v8, v8, v150
	v_add_f32_e32 v11, v11, v160
	v_add_f32_e32 v7, v7, v157
	v_add_f32_e32 v8, v8, v154
	v_fma_f32 v11, v131, v11, v128
	v_add_f32_e32 v7, v7, v161
	v_add_f32_e32 v8, v8, v158
	v_mul_f32_e32 v11, 0xbfb8aa3b, v11
	v_fma_f32 v7, v131, v7, v129
	v_add_f32_e32 v8, v8, v162
	v_exp_f32_e32 v11, v11
	v_mul_f32_e32 v7, 0xbfb8aa3b, v7
	v_fmac_f32_e32 v130, v131, v8
	v_exp_f32_e32 v7, v7
	v_mul_f32_e32 v8, 0xbfb8aa3b, v130
	v_exp_f32_e32 v8, v8
	s_cselect_b32 s10, 3, 1
	s_lshl_b32 s58, s20, 18
	s_lshl_b32 s4, s20, 19
	v_readlane_b32 s5, v254, 51
	s_add_u32 s14, s5, s4
	v_readlane_b32 s5, v254, 52
	v_add_f32_e32 v6, 1.0, v11
	s_addc_u32 s15, s5, 0
	v_readlane_b32 s5, v254, 53
	v_rcp_f32_e32 v134, v6
	v_add_f32_e32 v6, 1.0, v7
	s_add_u32 s16, s5, s4
	v_readlane_b32 s4, v254, 54
	v_rcp_f32_e32 v145, v6
	v_add_f32_e32 v6, 1.0, v8
	s_addc_u32 s17, s4, 0
	s_mul_i32 s4, s3, 0x210
	v_mul_f32_e32 v10, v166, v69
	v_rcp_f32_e32 v136, v6
	v_cvt_pk_bf16_f32 v128, v2, v3
	s_add_i32 s52, s4, 0
	v_lshlrev_b32_e32 v2, 4, v143
	s_movk_i32 s4, 0x70
	v_mul_f32_e32 v5, v5, v10
	v_cvt_pk_bf16_f32 v129, v4, v5
	s_waitcnt vmcnt(0) lgkmcnt(0)
	v_and_b32_e32 v3, 0x70, v2
	v_bitop3_b32 v138, v180, v2, s4 bitop3:0x78
	s_movk_i32 s4, 0x60
	s_lshl_b32 s12, s3, 12
	v_lshlrev_b32_e32 v2, 7, v143
	s_add_i32 s13, 0, 0x1c000
	v_lshlrev_b32_e32 v144, 2, v147
	v_mov_b32_e32 v173, v1
	v_mov_b32_e32 v177, v1
	v_mov_b32_e32 v135, v0
	v_mov_b32_e32 v193, v192
	v_mov_b32_e32 v146, 0
	s_mov_b32 s11, 0
	v_bitop3_b32 v140, v180, v3, 32 bitop3:0x36
	v_bitop3_b32 v141, v180, v3, 64 bitop3:0x36
	v_bitop3_b32 v142, v180, v3, s4 bitop3:0x36
	v_cmp_gt_u32_e64 s[4:5], 32, v155
	v_lshl_add_u32 v3, v143, 2, s13
	v_lshlrev_b32_e32 v4, 6, v147
	v_or3_b32 v2, s12, v2, v144
	s_add_i32 s60, 0, 0x14000
	v_mov_b32_e32 v175, v1
	v_mov_b32_e32 v179, v1
	v_permlane32_swap_b32_e32 v0, v135
	v_permlane32_swap_b32_e32 v192, v193
	v_xor_b32_e32 v148, 0x80000000, v195
	v_lshl_add_u64 v[130:131], s[14:15], 0, v[172:173]
	v_lshl_add_u64 v[132:133], s[14:15], 0, v[176:177]
	s_add_i32 s52, s52, 0x10800
	v_lshlrev_b32_e32 v137, 8, v143
	v_sub_u32_e32 v149, v143, v4
	v_add_u32_e32 v150, s60, v2
	s_mov_b64 s[42:43], 0
	s_xor_b64 s[12:13], s[4:5], -1
	v_add_u32_e32 v152, s59, v3
	s_mov_b32 s61, s54
	s_mov_b32 s53, s11
	v_mov_b32_e32 v2, 0
	v_mov_b32_e32 v3, v146
	v_mov_b32_e32 v4, v146
	v_mov_b32_e32 v5, v146
	v_mov_b32_e32 v6, v146
	v_mov_b32_e32 v7, v146
	v_mov_b32_e32 v8, v146
	v_mov_b32_e32 v9, v146
	v_mov_b32_e32 v10, v146
	v_mov_b32_e32 v11, v146
	v_mov_b32_e32 v12, v146
	v_mov_b32_e32 v13, v146
	v_mov_b32_e32 v14, v146
	v_mov_b32_e32 v15, v146
	v_mov_b32_e32 v16, v146
	v_mov_b32_e32 v17, v146
	v_mov_b32_e32 v18, 0
	v_mov_b32_e32 v19, v146
	v_mov_b32_e32 v20, v146
	v_mov_b32_e32 v21, v146
	v_mov_b32_e32 v22, v146
	v_mov_b32_e32 v23, v146
	v_mov_b32_e32 v24, v146
	v_mov_b32_e32 v25, v146
	v_mov_b32_e32 v26, v146
	v_mov_b32_e32 v27, v146
	v_mov_b32_e32 v28, v146
	v_mov_b32_e32 v29, v146
	v_mov_b32_e32 v30, v146
	v_mov_b32_e32 v31, v146
	v_mov_b32_e32 v32, v146
	v_mov_b32_e32 v33, v146
	v_mov_b32_e32 v34, 0
	v_mov_b32_e32 v35, v146
	v_mov_b32_e32 v36, v146
	v_mov_b32_e32 v37, v146
	v_mov_b32_e32 v38, v146
	v_mov_b32_e32 v39, v146
	v_mov_b32_e32 v40, v146
	v_mov_b32_e32 v41, v146
	v_mov_b32_e32 v42, v146
	v_mov_b32_e32 v43, v146
	v_mov_b32_e32 v44, v146
	v_mov_b32_e32 v45, v146
	v_mov_b32_e32 v46, v146
	v_mov_b32_e32 v47, v146
	v_mov_b32_e32 v48, v146
	v_mov_b32_e32 v49, v146
	v_mov_b32_e32 v50, 0
	v_mov_b32_e32 v51, v146
	v_mov_b32_e32 v52, v146
	v_mov_b32_e32 v53, v146
	v_mov_b32_e32 v54, v146
	v_mov_b32_e32 v55, v146
	v_mov_b32_e32 v56, v146
	v_mov_b32_e32 v57, v146
	v_mov_b32_e32 v58, v146
	v_mov_b32_e32 v59, v146
	v_mov_b32_e32 v60, v146
	v_mov_b32_e32 v61, v146
	v_mov_b32_e32 v62, v146
	v_mov_b32_e32 v63, v146
	v_mov_b32_e32 v64, v146
	v_mov_b32_e32 v65, v146
	v_and_b32_e32 v66, 8, v143
	v_lshlrev_b32_e32 v66, 4, v66
	v_xor_b32_e32 v138, v66, v138
	v_xor_b32_e32 v140, v66, v140
	v_xor_b32_e32 v141, v66, v141
	v_xor_b32_e32 v142, v66, v142
	s_barrier

.LBB0_1702:
	s_add_i32 s20, s47, s43
	v_lshl_add_u64 v[66:67], s[44:45], 0, v[174:175]
	s_mov_b32 m0, s20
	s_add_i32 s43, s61, 0xfffffbf1
	global_load_lds_dwordx4 v[66:67], off
	v_lshl_add_u64 v[66:67], s[44:45], 0, v[178:179]
	s_add_i32 m0, s20, 0x400
	s_add_i32 s20, s62, 0
	global_load_lds_dwordx4 v[66:67], off
	s_cmpk_lt_i32 s43, 0x80
	s_cselect_b64 s[44:45], -1, 0
	s_cmp_gt_i32 s61, 0x3fffffff
	s_cselect_b64 s[64:65], -1, 0
	s_or_b64 s[64:65], s[44:45], s[64:65]
	v_add_u32_e32 v66, s20, v137
	s_mov_b64 s[44:45], -1
	s_and_b64 vcc, exec, s[64:65]
	v_add_u32_e32 v157, v66, v138
	v_add_u32_e32 v156, v66, v140
	v_add_u32_e32 v154, v66, v141
	v_add_u32_e32 v153, v66, v142
	s_cbranch_vccnz .LBB0_1704
	v_mov_b32_e32 v66, s52
	ds_read_b32 v66, v66 offset:512
	s_waitcnt lgkmcnt(0)
	v_sub_f32_e32 v162, v66, v195
	ds_read_b128 v[66:69], v157 offset:32768
	ds_read_b128 v[82:85], v157 offset:40960
	ds_read_b128 v[204:207], v156 offset:32768
	ds_read_b128 v[212:215], v156 offset:40960
	ds_read_b128 v[220:223], v154 offset:32768
	ds_read_b128 v[228:231], v154 offset:40960
	ds_read_b128 v[236:239], v153 offset:32768
	ds_read_b128 v[244:247], v153 offset:40960
	v_xor_b32_e32 v196, 0x80, v157
	ds_read_b128 v[196:199], v196 offset:32768
	v_xor_b32_e32 v200, 0x80, v157
	ds_read_b128 v[200:203], v200 offset:40960
	v_xor_b32_e32 v208, 0x80, v156
	ds_read_b128 v[208:211], v208 offset:32768
	v_xor_b32_e32 v216, 0x80, v156
	ds_read_b128 v[216:219], v216 offset:40960
	v_xor_b32_e32 v224, 0x80, v154
	ds_read_b128 v[224:227], v224 offset:32768
	v_xor_b32_e32 v232, 0x80, v154
	ds_read_b128 v[232:235], v232 offset:40960
	v_xor_b32_e32 v240, 0x80, v153
	ds_read_b128 v[240:243], v240 offset:32768
	v_xor_b32_e32 v248, 0x80, v153
	ds_read_b128 v[248:251], v248 offset:40960
	s_waitcnt lgkmcnt(8)
	v_mfma_f32_32x32x16_bf16 v[66:81], v[66:69], v[98:101], 0
	v_mfma_f32_32x32x16_bf16 v[82:97], v[82:85], v[98:101], 0
	v_mfma_f32_32x32x16_bf16 v[66:81], v[204:207], v[102:105], v[66:81]
	v_mfma_f32_32x32x16_bf16 v[82:97], v[212:215], v[102:105], v[82:97]
	v_mfma_f32_32x32x16_bf16 v[66:81], v[220:223], v[106:109], v[66:81]
	v_mfma_f32_32x32x16_bf16 v[82:97], v[228:231], v[106:109], v[82:97]
	v_mfma_f32_32x32x16_bf16 v[66:81], v[236:239], v[110:113], v[66:81]
	v_mfma_f32_32x32x16_bf16 v[82:97], v[244:247], v[110:113], v[82:97]
	s_waitcnt lgkmcnt(0)
	v_mfma_f32_32x32x16_bf16 v[66:81], v[196:199], v[114:117], v[66:81]
	v_mfma_f32_32x32x16_bf16 v[82:97], v[200:203], v[114:117], v[82:97]
	v_mfma_f32_32x32x16_bf16 v[66:81], v[208:211], v[118:121], v[66:81]
	v_mfma_f32_32x32x16_bf16 v[82:97], v[216:219], v[118:121], v[82:97]
	v_mfma_f32_32x32x16_bf16 v[66:81], v[224:227], v[122:125], v[66:81]
	v_mfma_f32_32x32x16_bf16 v[82:97], v[232:235], v[122:125], v[82:97]
	v_mfma_f32_32x32x16_bf16 v[66:81], v[240:243], v[126:129], v[66:81]
	v_mfma_f32_32x32x16_bf16 v[82:97], v[248:251], v[126:129], v[82:97]
	s_mov_b64 s[44:45], 0
.LBB0_1704:
	s_andn2_b64 vcc, exec, s[44:45]
	s_cbranch_vccnz .LBB0_1706
	s_nop 7
	v_add_u32_e32 v66, s61, v149
	v_subrev_u32_e32 v67, 31, v66
	v_add_u32_e32 v68, 0xfffffde1, v66
	v_subrev_u32_e32 v71, 47, v66
	v_add_u32_e32 v72, 0xfffffdd1, v66
	v_subrev_u32_e32 v75, 63, v66
	v_add_u32_e32 v76, 0xfffffdc1, v66
	v_add_u32_e32 v79, 0xffffffb1, v66
	v_add_u32_e32 v80, 0xfffffdb1, v66
	v_med3_i32 v69, v67, 0, v184
	v_med3_i32 v70, v68, 0, v184
	v_med3_i32 v73, v71, 0, v184
	v_med3_i32 v74, v72, 0, v184
	v_med3_i32 v77, v75, 0, v184
	v_med3_i32 v78, v76, 0, v184
	v_med3_i32 v81, v79, 0, v184
	v_med3_i32 v82, v80, 0, v184
	v_lshl_add_u32 v69, v69, 2, s52
	v_lshl_add_u32 v70, v70, 2, s52
	v_lshl_add_u32 v73, v73, 2, s52
	v_lshl_add_u32 v74, v74, 2, s52
	v_lshl_add_u32 v77, v77, 2, s52
	v_lshl_add_u32 v78, v78, 2, s52
	v_lshl_add_u32 v81, v81, 2, s52
	v_lshl_add_u32 v82, v82, 2, s52
	v_add_u32_e32 v86, 0xffffff61, v66
	v_add_u32_e32 v89, 0xfffffd51, v66
	v_add_u32_e32 v91, 0xffffff41, v66
	v_add_u32_e32 v92, 0xfffffd41, v66
	v_add_u32_e32 v95, 0xffffff31, v66
	v_add_u32_e32 v96, 0xfffffd31, v66
	ds_read_b32 v69, v69
	ds_read_b32 v70, v70
	ds_read_b32 v73, v73
	ds_read_b32 v74, v74
	ds_read_b32 v77, v77
	ds_read_b32 v78, v78
	ds_read_b32 v81, v81
	ds_read_b32 v85, v82
	v_add_u32_e32 v87, 0xfffffd61, v66
	v_med3_i32 v82, v86, 0, v184
	v_add_u32_e32 v88, 0xffffff51, v66
	v_med3_i32 v90, v89, 0, v184
	v_med3_i32 v93, v91, 0, v184
	v_med3_i32 v94, v92, 0, v184
	v_med3_i32 v97, v95, 0, v184
	v_med3_i32 v158, v96, 0, v184
	v_lshl_add_u32 v82, v82, 2, s52
	v_med3_i32 v83, v87, 0, v184
	v_med3_i32 v84, v88, 0, v184
	v_lshl_add_u32 v90, v90, 2, s52
	v_lshl_add_u32 v93, v93, 2, s52
	v_lshl_add_u32 v94, v94, 2, s52
	v_lshl_add_u32 v97, v97, 2, s52
	v_lshl_add_u32 v158, v158, 2, s52
	v_add_u32_e32 v162, 0xfffffee1, v66
	v_add_u32_e32 v166, 0xfffffcd1, v66
	v_add_u32_e32 v196, 0xfffffec1, v66
	v_add_u32_e32 v197, 0xfffffcc1, v66
	v_add_u32_e32 v200, 0xfffffeb1, v66
	v_add_u32_e32 v201, 0xfffffcb1, v66
	v_lshl_add_u32 v83, v83, 2, s52
	v_lshl_add_u32 v84, v84, 2, s52
	ds_read_b32 v159, v82
	ds_read_b32 v160, v83
	ds_read_b32 v161, v84
	ds_read_b32 v90, v90
	ds_read_b32 v93, v93
	ds_read_b32 v94, v94
	ds_read_b32 v97, v97
	ds_read_b32 v158, v158
	v_add_u32_e32 v164, 0xfffffce1, v66
	v_med3_i32 v82, v162, 0, v184
	v_add_u32_e32 v165, 0xfffffed1, v66
	v_med3_i32 v167, v166, 0, v184
	v_med3_i32 v198, v196, 0, v184
	v_med3_i32 v199, v197, 0, v184
	v_med3_i32 v202, v200, 0, v184
	v_med3_i32 v203, v201, 0, v184
	v_lshl_add_u32 v82, v82, 2, s52
	v_med3_i32 v83, v164, 0, v184
	v_med3_i32 v84, v165, 0, v184
	v_lshl_add_u32 v167, v167, 2, s52
	v_lshl_add_u32 v198, v198, 2, s52
	v_lshl_add_u32 v199, v199, 2, s52
	v_lshl_add_u32 v202, v202, 2, s52
	v_lshl_add_u32 v203, v203, 2, s52
	v_add_u32_e32 v207, 0xfffffe61, v66
	v_add_u32_e32 v210, 0xfffffc51, v66
	v_add_u32_e32 v212, 0xfffffe41, v66
	v_add_u32_e32 v213, 0xfffffc41, v66
	v_add_u32_e32 v216, 0xfffffe31, v66
	v_add_u32_e32 v217, 0xfffffc31, v66
	v_lshl_add_u32 v83, v83, 2, s52
	v_lshl_add_u32 v84, v84, 2, s52
	ds_read_b32 v204, v82
	ds_read_b32 v205, v83
	ds_read_b32 v206, v84
	ds_read_b32 v167, v167
	ds_read_b32 v198, v198
	ds_read_b32 v199, v199
	ds_read_b32 v202, v202
	ds_read_b32 v203, v203
	v_add_u32_e32 v208, 0xfffffc61, v66
	v_med3_i32 v82, v207, 0, v184
	v_add_u32_e32 v209, 0xfffffe51, v66
	v_med3_i32 v211, v210, 0, v184
	v_med3_i32 v214, v212, 0, v184
	v_med3_i32 v215, v213, 0, v184
	v_med3_i32 v66, v216, 0, v184
	v_med3_i32 v218, v217, 0, v184
	v_lshl_add_u32 v82, v82, 2, s52
	v_med3_i32 v83, v208, 0, v184
	v_med3_i32 v84, v209, 0, v184
	v_lshl_add_u32 v211, v211, 2, s52
	v_lshl_add_u32 v214, v214, 2, s52
	v_lshl_add_u32 v215, v215, 2, s52
	v_lshl_add_u32 v66, v66, 2, s52
	v_lshl_add_u32 v218, v218, 2, s52
	v_cmp_gt_u32_e32 vcc, 2.0, v67
	v_lshl_add_u32 v83, v83, 2, s52
	v_lshl_add_u32 v84, v84, 2, s52
	ds_read_b32 v219, v82
	ds_read_b32 v220, v83
	ds_read_b32 v221, v84
	ds_read_b32 v211, v211
	ds_read_b32 v214, v214
	ds_read_b32 v215, v215
	ds_read_b32 v222, v66
	ds_read_b32 v218, v218
	s_waitcnt lgkmcnt(0)
	v_cndmask_b32_e32 v66, v186, v69, vcc
	v_cmp_gt_u32_e32 vcc, 2.0, v68
	s_waitcnt lgkmcnt(0)
	s_nop 1
	v_cndmask_b32_e32 v82, v186, v70, vcc
	v_cmp_gt_u32_e32 vcc, 2.0, v71
	s_nop 1
	v_cndmask_b32_e32 v67, v186, v73, vcc
	v_cmp_gt_u32_e32 vcc, 2.0, v72
	s_nop 1
	v_cndmask_b32_e32 v83, v186, v74, vcc
	v_cmp_gt_u32_e32 vcc, 2.0, v75
	s_nop 1
	v_cndmask_b32_e32 v68, v186, v77, vcc
	v_cmp_gt_u32_e32 vcc, 2.0, v76
	s_nop 1
	v_cndmask_b32_e32 v84, v186, v78, vcc
	v_cmp_gt_u32_e32 vcc, 2.0, v79
	s_nop 1
	v_cndmask_b32_e32 v69, v186, v81, vcc
	v_cmp_gt_u32_e32 vcc, 2.0, v80
	s_nop 1
	v_cndmask_b32_e32 v85, v186, v85, vcc
	v_cmp_gt_u32_e32 vcc, 2.0, v86
	s_nop 1
	v_cndmask_b32_e32 v70, v186, v159, vcc
	v_cmp_gt_u32_e32 vcc, 2.0, v87
	s_nop 1
	v_cndmask_b32_e32 v86, v186, v160, vcc
	v_cmp_gt_u32_e32 vcc, 2.0, v88
	s_nop 1
	v_cndmask_b32_e32 v71, v186, v161, vcc
	v_cmp_gt_u32_e32 vcc, 2.0, v89
	s_nop 1
	v_cndmask_b32_e32 v87, v186, v90, vcc
	v_cmp_gt_u32_e32 vcc, 2.0, v91
	s_nop 1
	v_cndmask_b32_e32 v72, v186, v93, vcc
	v_cmp_gt_u32_e32 vcc, 2.0, v92
	s_nop 1
	v_cndmask_b32_e32 v88, v186, v94, vcc
	v_cmp_gt_u32_e32 vcc, 2.0, v95
	s_nop 1
	v_cndmask_b32_e32 v73, v186, v97, vcc
	v_cmp_gt_u32_e32 vcc, 2.0, v96
	s_nop 1
	v_cndmask_b32_e32 v89, v186, v158, vcc
	v_cmp_gt_u32_e32 vcc, 2.0, v162
	s_nop 1
	v_cndmask_b32_e32 v74, v186, v204, vcc
	v_cmp_gt_u32_e32 vcc, 2.0, v164
	s_nop 1
	v_cndmask_b32_e32 v90, v186, v205, vcc
	v_cmp_gt_u32_e32 vcc, 2.0, v165
	s_nop 1
	v_cndmask_b32_e32 v75, v186, v206, vcc
	v_cmp_gt_u32_e32 vcc, 2.0, v166
	s_nop 1
	v_cndmask_b32_e32 v91, v186, v167, vcc
	v_cmp_gt_u32_e32 vcc, 2.0, v196
	s_nop 1
	v_cndmask_b32_e32 v76, v186, v198, vcc
	v_cmp_gt_u32_e32 vcc, 2.0, v197
	s_nop 1
	v_cndmask_b32_e32 v92, v186, v199, vcc
	v_cmp_gt_u32_e32 vcc, 2.0, v200
	s_nop 1
	v_cndmask_b32_e32 v77, v186, v202, vcc
	v_cmp_gt_u32_e32 vcc, 2.0, v201
	s_nop 1
	v_cndmask_b32_e32 v93, v186, v203, vcc
	v_cmp_gt_u32_e32 vcc, 2.0, v207
	s_nop 1
	v_cndmask_b32_e32 v78, v186, v219, vcc
	v_cmp_gt_u32_e32 vcc, 2.0, v208
	s_nop 1
	v_cndmask_b32_e32 v94, v186, v220, vcc
	v_cmp_gt_u32_e32 vcc, 2.0, v209
	s_nop 1
	v_cndmask_b32_e32 v79, v186, v221, vcc
	v_cmp_gt_u32_e32 vcc, 2.0, v210
	s_nop 1
	v_cndmask_b32_e32 v95, v186, v211, vcc
	v_cmp_gt_u32_e32 vcc, 2.0, v212
	s_nop 1
	v_cndmask_b32_e32 v80, v186, v214, vcc
	v_cmp_gt_u32_e32 vcc, 2.0, v213
	s_nop 1
	v_cndmask_b32_e32 v96, v186, v215, vcc
	v_cmp_gt_u32_e32 vcc, 2.0, v216
	s_nop 1
	v_cndmask_b32_e32 v81, v186, v222, vcc
	v_cmp_gt_u32_e32 vcc, 2.0, v217
	s_nop 1
	v_cndmask_b32_e32 v97, v186, v218, vcc
	ds_read_b128 v[196:199], v157 offset:32768
	v_xor_b32_e32 v200, 0x80, v157
	ds_read_b128 v[200:203], v200 offset:32768
	ds_read_b128 v[204:207], v157 offset:40960
	v_xor_b32_e32 v208, 0x80, v157
	ds_read_b128 v[208:211], v208 offset:40960
	ds_read_b128 v[212:215], v156 offset:32768
	v_xor_b32_e32 v216, 0x80, v156
	ds_read_b128 v[216:219], v216 offset:32768
	ds_read_b128 v[220:223], v156 offset:40960
	v_xor_b32_e32 v224, 0x80, v156
	ds_read_b128 v[224:227], v224 offset:40960
	ds_read_b128 v[228:231], v154 offset:32768
	v_xor_b32_e32 v232, 0x80, v154
	ds_read_b128 v[232:235], v232 offset:32768
	ds_read_b128 v[236:239], v154 offset:40960
	v_xor_b32_e32 v240, 0x80, v154
	ds_read_b128 v[240:243], v240 offset:40960
	ds_read_b128 v[244:247], v153 offset:32768
	v_xor_b32_e32 v248, 0x80, v153
	ds_read_b128 v[248:251], v248 offset:32768
	ds_read_b128 v[156:159], v153 offset:40960
	v_xor_b32_e32 v164, 0x80, v153
	ds_read_b128 v[164:167], v164 offset:40960
	s_waitcnt lgkmcnt(8)
	s_waitcnt lgkmcnt(0)
	v_mfma_f32_32x32x16_bf16 v[66:81], v[196:199], v[98:101], v[66:81]
	v_mfma_f32_32x32x16_bf16 v[82:97], v[204:207], v[98:101], v[82:97]
	v_mfma_f32_32x32x16_bf16 v[66:81], v[212:215], v[102:105], v[66:81]
	v_mfma_f32_32x32x16_bf16 v[82:97], v[220:223], v[102:105], v[82:97]
	v_mfma_f32_32x32x16_bf16 v[66:81], v[228:231], v[106:109], v[66:81]
	v_mfma_f32_32x32x16_bf16 v[82:97], v[236:239], v[106:109], v[82:97]
	v_mfma_f32_32x32x16_bf16 v[66:81], v[244:247], v[110:113], v[66:81]
	v_mfma_f32_32x32x16_bf16 v[82:97], v[156:159], v[110:113], v[82:97]
	s_waitcnt lgkmcnt(0)
	v_mfma_f32_32x32x16_bf16 v[66:81], v[200:203], v[114:117], v[66:81]
	v_mfma_f32_32x32x16_bf16 v[82:97], v[208:211], v[114:117], v[82:97]
	v_mfma_f32_32x32x16_bf16 v[66:81], v[216:219], v[118:121], v[66:81]
	v_mfma_f32_32x32x16_bf16 v[82:97], v[224:227], v[118:121], v[82:97]
	v_mfma_f32_32x32x16_bf16 v[66:81], v[232:235], v[122:125], v[66:81]
	v_mfma_f32_32x32x16_bf16 v[82:97], v[240:243], v[122:125], v[82:97]
	v_mfma_f32_32x32x16_bf16 v[66:81], v[248:251], v[126:129], v[66:81]
	v_mfma_f32_32x32x16_bf16 v[82:97], v[164:167], v[126:129], v[82:97]
	v_mov_b32_e32 v162, v148

.LBB0_1984:
	s_or_b64 exec, exec, s[10:11]
	v_lshlrev_b32_e64 v0, v68, 1
	v_and_b32_e32 v0, v0, v154
	v_lshlrev_b32_e32 v180, 6, v68
	v_cmp_eq_u32_e32 vcc, 0, v0
	v_cmp_ne_u32_e64 s[10:11], 0, v0
	v_sub_u32_e32 v0, s54, v180
	v_sub_u32_e32 v66, s60, v180
	s_movk_i32 s8, 0x7f
	s_lshl_b32 s20, s53, 14
	v_cmp_lt_i32_e64 s[12:13], s8, v0
	v_cmp_gt_i32_e64 s[8:9], 2.0, v66
	s_add_i32 s62, s20, 0
	s_and_b64 s[12:13], s[12:13], s[8:9]
	s_and_saveexec_b64 s[44:45], s[12:13]
	s_xor_b64 s[12:13], exec, s[44:45]
	s_cbranch_execz .LBB0_1988
	v_mov_b32_e32 v0, s52
	ds_read_b32 v0, v0 offset:512
	v_add_u32_e32 v66, s62, v137
	v_add_u32_e32 v74, v66, v138
	v_add_u32_e32 v75, v66, v140
	v_add_u32_e32 v76, v66, v141
	v_add_u32_e32 v77, v66, v142
	ds_read_b128 v[66:69], v74 offset:32768
	ds_read_b128 v[70:73], v74 offset:40960
	ds_read_b128 v[194:197], v75 offset:32768
	ds_read_b128 v[202:205], v75 offset:40960
	ds_read_b128 v[210:213], v76 offset:32768
	ds_read_b128 v[218:221], v76 offset:40960
	ds_read_b128 v[226:229], v77 offset:32768
	ds_read_b128 v[234:237], v77 offset:40960
	v_xor_b32_e32 v158, 0x80, v74
	ds_read_b128 v[158:161], v158 offset:32768
	v_xor_b32_e32 v164, 0x80, v74
	ds_read_b128 v[164:167], v164 offset:40960
	v_xor_b32_e32 v198, 0x80, v75
	ds_read_b128 v[198:201], v198 offset:32768
	v_xor_b32_e32 v206, 0x80, v75
	ds_read_b128 v[206:209], v206 offset:40960
	v_xor_b32_e32 v214, 0x80, v76
	ds_read_b128 v[214:217], v214 offset:32768
	v_xor_b32_e32 v222, 0x80, v76
	ds_read_b128 v[222:225], v222 offset:40960
	v_xor_b32_e32 v230, 0x80, v77
	ds_read_b128 v[230:233], v230 offset:32768
	v_xor_b32_e32 v238, 0x80, v77
	ds_read_b128 v[238:241], v238 offset:40960
	s_waitcnt lgkmcnt(8)
	v_mfma_f32_32x32x16_bf16 v[82:97], v[66:69], v[98:101], 0
	v_mfma_f32_32x32x16_bf16 v[66:81], v[70:73], v[98:101], 0
	v_mfma_f32_32x32x16_bf16 v[82:97], v[194:197], v[102:105], v[82:97]
	v_mfma_f32_32x32x16_bf16 v[66:81], v[202:205], v[102:105], v[66:81]
	v_mfma_f32_32x32x16_bf16 v[82:97], v[210:213], v[106:109], v[82:97]
	v_mfma_f32_32x32x16_bf16 v[66:81], v[218:221], v[106:109], v[66:81]
	v_mfma_f32_32x32x16_bf16 v[82:97], v[226:229], v[110:113], v[82:97]
	v_mfma_f32_32x32x16_bf16 v[66:81], v[234:237], v[110:113], v[66:81]
	s_waitcnt lgkmcnt(0)
	v_mfma_f32_32x32x16_bf16 v[82:97], v[158:161], v[114:117], v[82:97]
	v_mfma_f32_32x32x16_bf16 v[66:81], v[164:167], v[114:117], v[66:81]
	v_mfma_f32_32x32x16_bf16 v[82:97], v[198:201], v[118:121], v[82:97]
	v_mfma_f32_32x32x16_bf16 v[66:81], v[206:209], v[118:121], v[66:81]
	v_mfma_f32_32x32x16_bf16 v[82:97], v[214:217], v[122:125], v[82:97]
	v_mfma_f32_32x32x16_bf16 v[66:81], v[222:225], v[122:125], v[66:81]
	v_mfma_f32_32x32x16_bf16 v[82:97], v[230:233], v[126:129], v[82:97]
	v_mfma_f32_32x32x16_bf16 v[66:81], v[238:241], v[126:129], v[66:81]
	v_sub_f32_e32 v0, v0, v153
	v_cndmask_b32_e64 v0, v186, v0, s[10:11]
.LBB0_1988:
	s_andn2_saveexec_b64 s[10:11], s[12:13]
	s_cbranch_execz .LBB0_1974
	s_nop 9
	v_add_u32_e32 v66, s62, v137
	v_cndmask_b32_e64 v0, -v153, v186, vcc
	v_add_u32_e32 v162, v66, v138
	v_add_u32_e32 v161, v66, v140
	v_add_u32_e32 v160, v66, v141
	v_add_u32_e32 v158, v66, v142
	s_and_saveexec_b64 s[12:13], s[8:9]
	s_xor_b64 s[8:9], exec, s[12:13]
	s_cbranch_execz .LBB0_1991
	v_sub_u32_e32 v0, v180, v150
	v_lshl_add_u32 v0, v0, 2, v152
	v_add_u32_e32 v66, 0x400, v0
	v_add_u32_e32 v68, 0x408, v0
	v_add_u32_e32 v70, 0x420, v0
	v_add_u32_e32 v72, 0x428, v0
	v_add_u32_e32 v74, 0x440, v0
	v_add_u32_e32 v76, 0x448, v0
	v_add_u32_e32 v78, 0x460, v0
	v_add_u32_e32 v80, 0x468, v0
	ds_read2_b32 v[82:83], v0 offset0:224 offset1:225
	ds_read2_b32 v[84:85], v0 offset0:226 offset1:227
	ds_read2_b32 v[86:87], v0 offset0:232 offset1:233
	ds_read2_b32 v[88:89], v0 offset0:234 offset1:235
	ds_read2_b32 v[66:67], v66 offset1:1
	ds_read2_b32 v[68:69], v68 offset1:1
	ds_read2_b32 v[70:71], v70 offset1:1
	ds_read2_b32 v[72:73], v72 offset1:1
	ds_read2_b32 v[90:91], v0 offset0:240 offset1:241
	ds_read2_b32 v[92:93], v0 offset0:242 offset1:243
	ds_read2_b32 v[94:95], v0 offset0:248 offset1:249
	ds_read2_b32 v[96:97], v0 offset0:250 offset1:251
	ds_read2_b32 v[74:75], v74 offset1:1
	ds_read2_b32 v[76:77], v76 offset1:1
	ds_read2_b32 v[78:79], v78 offset1:1
	ds_read2_b32 v[80:81], v80 offset1:1
	v_cndmask_b32_e64 v0, -v153, v186, vcc
	ds_read_b128 v[164:167], v162 offset:32768
	ds_read_b128 v[198:201], v162 offset:40960
	ds_read_b128 v[206:209], v161 offset:32768
	ds_read_b128 v[214:217], v161 offset:40960
	ds_read_b128 v[222:225], v160 offset:32768
	ds_read_b128 v[230:233], v160 offset:40960
	ds_read_b128 v[238:241], v158 offset:32768
	ds_read_b128 v[246:249], v158 offset:40960
	v_xor_b32_e32 v194, 0x80, v162
	ds_read_b128 v[194:197], v194 offset:32768
	v_xor_b32_e32 v202, 0x80, v162
	ds_read_b128 v[202:205], v202 offset:40960
	v_xor_b32_e32 v210, 0x80, v161
	ds_read_b128 v[210:213], v210 offset:32768
	v_xor_b32_e32 v218, 0x80, v161
	ds_read_b128 v[218:221], v218 offset:40960
	v_xor_b32_e32 v226, 0x80, v160
	ds_read_b128 v[226:229], v226 offset:32768
	v_xor_b32_e32 v234, 0x80, v160
	ds_read_b128 v[234:237], v234 offset:40960
	v_xor_b32_e32 v242, 0x80, v158
	ds_read_b128 v[242:245], v242 offset:32768
	v_xor_b32_e32 v158, 0x80, v158
	ds_read_b128 v[158:161], v158 offset:40960
	s_waitcnt lgkmcnt(8)
	v_mfma_f32_32x32x16_bf16 v[82:97], v[164:167], v[98:101], v[82:97]
	v_mfma_f32_32x32x16_bf16 v[66:81], v[198:201], v[98:101], v[66:81]
	v_mfma_f32_32x32x16_bf16 v[82:97], v[206:209], v[102:105], v[82:97]
	v_mfma_f32_32x32x16_bf16 v[66:81], v[214:217], v[102:105], v[66:81]
	v_mfma_f32_32x32x16_bf16 v[82:97], v[222:225], v[106:109], v[82:97]
	v_mfma_f32_32x32x16_bf16 v[66:81], v[230:233], v[106:109], v[66:81]
	v_mfma_f32_32x32x16_bf16 v[82:97], v[238:241], v[110:113], v[82:97]
	v_mfma_f32_32x32x16_bf16 v[66:81], v[246:249], v[110:113], v[66:81]
	s_waitcnt lgkmcnt(0)
	v_mfma_f32_32x32x16_bf16 v[82:97], v[194:197], v[114:117], v[82:97]
	v_mfma_f32_32x32x16_bf16 v[66:81], v[202:205], v[114:117], v[66:81]
	v_mfma_f32_32x32x16_bf16 v[82:97], v[210:213], v[118:121], v[82:97]
	v_mfma_f32_32x32x16_bf16 v[66:81], v[218:221], v[118:121], v[66:81]
	v_mfma_f32_32x32x16_bf16 v[82:97], v[226:229], v[122:125], v[82:97]
	v_mfma_f32_32x32x16_bf16 v[66:81], v[234:237], v[122:125], v[66:81]
	v_mfma_f32_32x32x16_bf16 v[82:97], v[242:245], v[126:129], v[82:97]
	v_mfma_f32_32x32x16_bf16 v[66:81], v[158:161], v[126:129], v[66:81]
.LBB0_1991:
	s_andn2_saveexec_b64 s[8:9], s[8:9]
	s_cbranch_execz .LBB0_1973
	s_nop 9
	v_or_b32_e32 v66, v180, v144
	v_sub_u32_e32 v66, v150, v66
	v_subrev_u32_e32 v67, 32, v66
	v_add_u32_e32 v70, -1, v66
	v_subrev_u32_e32 v71, 33, v66
	v_add_u32_e32 v74, -2, v66
	v_subrev_u32_e32 v75, 34, v66
	v_add_u32_e32 v78, -3, v66
	v_subrev_u32_e32 v79, 35, v66
	v_add_u32_e32 v86, -8, v66
	v_add_u32_e32 v90, -10, v66
	v_subrev_u32_e32 v91, 42, v66
	v_add_u32_e32 v94, -11, v66
	v_subrev_u32_e32 v95, 43, v66
	v_med3_i32 v68, v66, 0, v184
	v_med3_i32 v69, v67, 0, v184
	v_med3_i32 v72, v70, 0, v184
	v_med3_i32 v73, v71, 0, v184
	v_med3_i32 v76, v74, 0, v184
	v_med3_i32 v77, v75, 0, v184
	v_med3_i32 v80, v78, 0, v184
	v_med3_i32 v81, v79, 0, v184
	v_subrev_u32_e32 v87, 40, v66
	v_med3_i32 v82, v86, 0, v184
	v_add_u32_e32 v88, -9, v66
	v_subrev_u32_e32 v89, 41, v66
	v_med3_i32 v92, v90, 0, v184
	v_med3_i32 v93, v91, 0, v184
	v_med3_i32 v96, v94, 0, v184
	v_med3_i32 v97, v95, 0, v184
	v_lshl_add_u32 v68, v68, 2, s52
	v_lshl_add_u32 v69, v69, 2, s52
	v_lshl_add_u32 v72, v72, 2, s52
	v_lshl_add_u32 v73, v73, 2, s52
	v_lshl_add_u32 v76, v76, 2, s52
	v_lshl_add_u32 v77, v77, 2, s52
	v_lshl_add_u32 v80, v80, 2, s52
	v_lshl_add_u32 v81, v81, 2, s52
	v_lshl_add_u32 v82, v82, 2, s52
	v_med3_i32 v83, v87, 0, v184
	v_med3_i32 v84, v88, 0, v184
	v_med3_i32 v85, v89, 0, v184
	v_lshl_add_u32 v92, v92, 2, s52
	v_lshl_add_u32 v93, v93, 2, s52
	v_lshl_add_u32 v96, v96, 2, s52
	v_lshl_add_u32 v97, v97, 2, s52
	v_add_u32_e32 v167, -16, v66
	v_subrev_u32_e32 v196, 18, v66
	v_subrev_u32_e32 v197, 50, v66
	v_subrev_u32_e32 v200, 19, v66
	v_subrev_u32_e32 v201, 51, v66
	ds_read_b32 v68, v68
	ds_read_b32 v69, v69
	ds_read_b32 v72, v72
	ds_read_b32 v73, v73
	ds_read_b32 v76, v76
	ds_read_b32 v77, v77
	ds_read_b32 v80, v80
	ds_read_b32 v81, v81
	v_lshl_add_u32 v83, v83, 2, s52
	v_lshl_add_u32 v84, v84, 2, s52
	v_lshl_add_u32 v85, v85, 2, s52
	ds_read_b32 v159, v82
	ds_read_b32 v164, v83
	ds_read_b32 v165, v84
	ds_read_b32 v166, v85
	ds_read_b32 v92, v92
	ds_read_b32 v93, v93
	ds_read_b32 v96, v96
	ds_read_b32 v97, v97
	v_subrev_u32_e32 v180, 48, v66
	v_med3_i32 v82, v167, 0, v184
	v_subrev_u32_e32 v194, 17, v66
	v_subrev_u32_e32 v195, 49, v66
	v_med3_i32 v198, v196, 0, v184
	v_med3_i32 v199, v197, 0, v184
	v_med3_i32 v202, v200, 0, v184
	v_med3_i32 v203, v201, 0, v184
	v_lshl_add_u32 v82, v82, 2, s52
	v_med3_i32 v83, v180, 0, v184
	v_med3_i32 v84, v194, 0, v184
	v_med3_i32 v85, v195, 0, v184
	v_lshl_add_u32 v198, v198, 2, s52
	v_lshl_add_u32 v199, v199, 2, s52
	v_lshl_add_u32 v202, v202, 2, s52
	v_lshl_add_u32 v203, v203, 2, s52
	v_subrev_u32_e32 v208, 24, v66
	v_subrev_u32_e32 v212, 26, v66
	v_subrev_u32_e32 v213, 58, v66
	v_subrev_u32_e32 v216, 27, v66
	v_subrev_u32_e32 v217, 59, v66
	v_lshl_add_u32 v83, v83, 2, s52
	v_lshl_add_u32 v84, v84, 2, s52
	v_lshl_add_u32 v85, v85, 2, s52
	ds_read_b32 v204, v82
	ds_read_b32 v205, v83
	ds_read_b32 v206, v84
	ds_read_b32 v207, v85
	ds_read_b32 v198, v198
	ds_read_b32 v199, v199
	ds_read_b32 v202, v202
	ds_read_b32 v203, v203
	v_subrev_u32_e32 v209, 56, v66
	v_med3_i32 v82, v208, 0, v184
	v_subrev_u32_e32 v210, 25, v66
	v_subrev_u32_e32 v211, 57, v66
	v_med3_i32 v214, v212, 0, v184
	v_med3_i32 v215, v213, 0, v184
	v_med3_i32 v218, v216, 0, v184
	v_med3_i32 v219, v217, 0, v184
	v_lshl_add_u32 v82, v82, 2, s52
	v_med3_i32 v83, v209, 0, v184
	v_med3_i32 v84, v210, 0, v184
	v_med3_i32 v85, v211, 0, v184
	v_lshl_add_u32 v214, v214, 2, s52
	v_lshl_add_u32 v215, v215, 2, s52
	v_lshl_add_u32 v218, v218, 2, s52
	v_lshl_add_u32 v219, v219, 2, s52
	v_cmp_gt_u32_e32 vcc, 2.0, v66
	v_lshl_add_u32 v83, v83, 2, s52
	v_lshl_add_u32 v84, v84, 2, s52
	v_lshl_add_u32 v85, v85, 2, s52
	ds_read_b32 v220, v82
	ds_read_b32 v221, v83
	ds_read_b32 v222, v84
	ds_read_b32 v223, v85
	ds_read_b32 v214, v214
	ds_read_b32 v215, v215
	ds_read_b32 v218, v218
	ds_read_b32 v219, v219
	s_waitcnt lgkmcnt(0)
	v_cndmask_b32_e32 v82, v186, v68, vcc
	v_cmp_gt_u32_e32 vcc, 2.0, v67
	s_waitcnt lgkmcnt(0)
	s_nop 1
	v_cndmask_b32_e32 v66, v186, v69, vcc
	v_cmp_gt_u32_e32 vcc, 2.0, v70
	s_nop 1
	v_cndmask_b32_e32 v83, v186, v72, vcc
	v_cmp_gt_u32_e32 vcc, 2.0, v71
	s_nop 1
	v_cndmask_b32_e32 v67, v186, v73, vcc
	v_cmp_gt_u32_e32 vcc, 2.0, v74
	s_nop 1
	v_cndmask_b32_e32 v84, v186, v76, vcc
	v_cmp_gt_u32_e32 vcc, 2.0, v75
	s_nop 1
	v_cndmask_b32_e32 v68, v186, v77, vcc
	v_cmp_gt_u32_e32 vcc, 2.0, v78
	s_nop 1
	v_cndmask_b32_e32 v85, v186, v80, vcc
	v_cmp_gt_u32_e32 vcc, 2.0, v79
	s_nop 1
	v_cndmask_b32_e32 v69, v186, v81, vcc
	v_cmp_gt_u32_e32 vcc, 2.0, v86
	s_nop 1
	v_cndmask_b32_e32 v86, v186, v159, vcc
	v_cmp_gt_u32_e32 vcc, 2.0, v87
	s_nop 1
	v_cndmask_b32_e32 v70, v186, v164, vcc
	v_cmp_gt_u32_e32 vcc, 2.0, v88
	s_nop 1
	v_cndmask_b32_e32 v87, v186, v165, vcc
	v_cmp_gt_u32_e32 vcc, 2.0, v89
	s_nop 1
	v_cndmask_b32_e32 v71, v186, v166, vcc
	v_cmp_gt_u32_e32 vcc, 2.0, v90
	s_nop 1
	v_cndmask_b32_e32 v88, v186, v92, vcc
	v_cmp_gt_u32_e32 vcc, 2.0, v91
	s_nop 1
	v_cndmask_b32_e32 v72, v186, v93, vcc
	v_cmp_gt_u32_e32 vcc, 2.0, v94
	s_nop 1
	v_cndmask_b32_e32 v89, v186, v96, vcc
	v_cmp_gt_u32_e32 vcc, 2.0, v95
	s_nop 1
	v_cndmask_b32_e32 v73, v186, v97, vcc
	v_cmp_gt_u32_e32 vcc, 2.0, v167
	s_nop 1
	v_cndmask_b32_e32 v90, v186, v204, vcc
	v_cmp_gt_u32_e32 vcc, 2.0, v180
	s_nop 1
	v_cndmask_b32_e32 v74, v186, v205, vcc
	v_cmp_gt_u32_e32 vcc, 2.0, v194
	s_nop 1
	v_cndmask_b32_e32 v91, v186, v206, vcc
	v_cmp_gt_u32_e32 vcc, 2.0, v195
	s_nop 1
	v_cndmask_b32_e32 v75, v186, v207, vcc
	v_cmp_gt_u32_e32 vcc, 2.0, v196
	s_nop 1
	v_cndmask_b32_e32 v92, v186, v198, vcc
	v_cmp_gt_u32_e32 vcc, 2.0, v197
	s_nop 1
	v_cndmask_b32_e32 v76, v186, v199, vcc
	v_cmp_gt_u32_e32 vcc, 2.0, v200
	s_nop 1
	v_cndmask_b32_e32 v93, v186, v202, vcc
	v_cmp_gt_u32_e32 vcc, 2.0, v201
	s_nop 1
	v_cndmask_b32_e32 v77, v186, v203, vcc
	v_cmp_gt_u32_e32 vcc, 2.0, v208
	s_nop 1
	v_cndmask_b32_e32 v94, v186, v220, vcc
	v_cmp_gt_u32_e32 vcc, 2.0, v209
	s_nop 1
	v_cndmask_b32_e32 v78, v186, v221, vcc
	v_cmp_gt_u32_e32 vcc, 2.0, v210
	s_nop 1
	v_cndmask_b32_e32 v95, v186, v222, vcc
	v_cmp_gt_u32_e32 vcc, 2.0, v211
	s_nop 1
	v_cndmask_b32_e32 v79, v186, v223, vcc
	v_cmp_gt_u32_e32 vcc, 2.0, v212
	s_nop 1
	v_cndmask_b32_e32 v96, v186, v214, vcc
	v_cmp_gt_u32_e32 vcc, 2.0, v213
	s_nop 1
	v_cndmask_b32_e32 v80, v186, v215, vcc
	v_cmp_gt_u32_e32 vcc, 2.0, v216
	s_nop 1
	v_cndmask_b32_e32 v97, v186, v218, vcc
	v_cmp_gt_u32_e32 vcc, 2.0, v217
	s_nop 1
	v_cndmask_b32_e32 v81, v186, v219, vcc
	ds_read_b128 v[164:167], v162 offset:32768
	ds_read_b128 v[198:201], v162 offset:40960
	ds_read_b128 v[206:209], v161 offset:32768
	ds_read_b128 v[214:217], v161 offset:40960
	ds_read_b128 v[222:225], v160 offset:32768
	ds_read_b128 v[230:233], v160 offset:40960
	ds_read_b128 v[238:241], v158 offset:32768
	ds_read_b128 v[246:249], v158 offset:40960
	v_xor_b32_e32 v194, 0x80, v162
	ds_read_b128 v[194:197], v194 offset:32768
	v_xor_b32_e32 v202, 0x80, v162
	ds_read_b128 v[202:205], v202 offset:40960
	v_xor_b32_e32 v210, 0x80, v161
	ds_read_b128 v[210:213], v210 offset:32768
	v_xor_b32_e32 v218, 0x80, v161
	ds_read_b128 v[218:221], v218 offset:40960
	v_xor_b32_e32 v226, 0x80, v160
	ds_read_b128 v[226:229], v226 offset:32768
	v_xor_b32_e32 v234, 0x80, v160
	ds_read_b128 v[234:237], v234 offset:40960
	v_xor_b32_e32 v242, 0x80, v158
	ds_read_b128 v[242:245], v242 offset:32768
	v_xor_b32_e32 v158, 0x80, v158
	ds_read_b128 v[158:161], v158 offset:40960
	s_waitcnt lgkmcnt(8)
	v_mfma_f32_32x32x16_bf16 v[82:97], v[164:167], v[98:101], v[82:97]
	v_mfma_f32_32x32x16_bf16 v[66:81], v[198:201], v[98:101], v[66:81]
	v_mfma_f32_32x32x16_bf16 v[82:97], v[206:209], v[102:105], v[82:97]
	v_mfma_f32_32x32x16_bf16 v[66:81], v[214:217], v[102:105], v[66:81]
	v_mfma_f32_32x32x16_bf16 v[82:97], v[222:225], v[106:109], v[82:97]
	v_mfma_f32_32x32x16_bf16 v[66:81], v[230:233], v[106:109], v[66:81]
	v_mfma_f32_32x32x16_bf16 v[82:97], v[238:241], v[110:113], v[82:97]
	v_mfma_f32_32x32x16_bf16 v[66:81], v[246:249], v[110:113], v[66:81]
	s_waitcnt lgkmcnt(0)
	v_mfma_f32_32x32x16_bf16 v[82:97], v[194:197], v[114:117], v[82:97]
	v_mfma_f32_32x32x16_bf16 v[66:81], v[202:205], v[114:117], v[66:81]
	v_mfma_f32_32x32x16_bf16 v[82:97], v[210:213], v[118:121], v[82:97]
	v_mfma_f32_32x32x16_bf16 v[66:81], v[218:221], v[118:121], v[66:81]
	v_mfma_f32_32x32x16_bf16 v[82:97], v[226:229], v[122:125], v[82:97]
	v_mfma_f32_32x32x16_bf16 v[66:81], v[234:237], v[122:125], v[66:81]
	v_mfma_f32_32x32x16_bf16 v[82:97], v[242:245], v[126:129], v[82:97]
	v_mfma_f32_32x32x16_bf16 v[66:81], v[158:161], v[126:129], v[66:81]
	s_branch .LBB0_1973

.LBB0_2001:
	s_lshl_b32 s13, s61, 6
	s_sub_i32 s8, s54, s13
	s_sub_i32 s14, s60, s13
	s_cmpk_lt_i32 s8, 0x80
	s_cselect_b64 s[10:11], -1, 0
	s_cmpk_lt_i32 s14, 0x201
	s_cselect_b64 s[8:9], -1, 0
	s_cmpk_gt_i32 s14, 0x200
	v_add_u32_e32 v66, 0, v133
	s_cselect_b64 s[14:15], -1, 0
	s_or_b64 s[14:15], s[10:11], s[14:15]
	v_add_u32_e32 v66, v66, v137
	s_mov_b64 s[10:11], -1
	s_and_b64 vcc, exec, s[14:15]
	v_add_u32_e32 v153, v66, v138
	v_add_u32_e32 v145, v66, v140
	v_add_u32_e32 v135, v66, v141
	v_add_u32_e32 v134, v66, v142
	s_cbranch_vccnz .LBB0_2003
	v_mov_b32_e32 v154, s52
	ds_read_b32 v154, v154 offset:512
	ds_read_b128 v[66:69], v153 offset:32768
	ds_read_b128 v[70:73], v153 offset:40960
	ds_read_b128 v[190:193], v145 offset:32768
	ds_read_b128 v[198:201], v145 offset:40960
	ds_read_b128 v[206:209], v135 offset:32768
	ds_read_b128 v[214:217], v135 offset:40960
	ds_read_b128 v[222:225], v134 offset:32768
	ds_read_b128 v[230:233], v134 offset:40960
	v_xor_b32_e32 v156, 0x80, v153
	ds_read_b128 v[156:159], v156 offset:32768
	v_xor_b32_e32 v164, 0x80, v153
	ds_read_b128 v[164:167], v164 offset:40960
	v_xor_b32_e32 v194, 0x80, v145
	ds_read_b128 v[194:197], v194 offset:32768
	v_xor_b32_e32 v202, 0x80, v145
	ds_read_b128 v[202:205], v202 offset:40960
	v_xor_b32_e32 v210, 0x80, v135
	ds_read_b128 v[210:213], v210 offset:32768
	v_xor_b32_e32 v218, 0x80, v135
	ds_read_b128 v[218:221], v218 offset:40960
	v_xor_b32_e32 v226, 0x80, v134
	ds_read_b128 v[226:229], v226 offset:32768
	v_xor_b32_e32 v234, 0x80, v134
	ds_read_b128 v[234:237], v234 offset:40960
	s_waitcnt lgkmcnt(8)
	v_mfma_f32_32x32x16_bf16 v[82:97], v[66:69], v[98:101], 0
	v_mfma_f32_32x32x16_bf16 v[66:81], v[70:73], v[98:101], 0
	v_mfma_f32_32x32x16_bf16 v[82:97], v[190:193], v[102:105], v[82:97]
	v_mfma_f32_32x32x16_bf16 v[66:81], v[198:201], v[102:105], v[66:81]
	v_mfma_f32_32x32x16_bf16 v[82:97], v[206:209], v[106:109], v[82:97]
	v_mfma_f32_32x32x16_bf16 v[66:81], v[214:217], v[106:109], v[66:81]
	v_mfma_f32_32x32x16_bf16 v[82:97], v[222:225], v[110:113], v[82:97]
	v_mfma_f32_32x32x16_bf16 v[66:81], v[230:233], v[110:113], v[66:81]
	s_waitcnt lgkmcnt(0)
	v_mfma_f32_32x32x16_bf16 v[82:97], v[156:159], v[114:117], v[82:97]
	v_mfma_f32_32x32x16_bf16 v[66:81], v[164:167], v[114:117], v[66:81]
	v_mfma_f32_32x32x16_bf16 v[82:97], v[194:197], v[118:121], v[82:97]
	v_mfma_f32_32x32x16_bf16 v[66:81], v[202:205], v[118:121], v[66:81]
	v_mfma_f32_32x32x16_bf16 v[82:97], v[210:213], v[122:125], v[82:97]
	v_mfma_f32_32x32x16_bf16 v[66:81], v[218:221], v[122:125], v[66:81]
	v_mfma_f32_32x32x16_bf16 v[82:97], v[226:229], v[126:129], v[82:97]
	v_mfma_f32_32x32x16_bf16 v[66:81], v[234:237], v[126:129], v[66:81]
	v_sub_f32_e32 v154, v154, v131
	s_mov_b64 s[10:11], 0
.LBB0_2003:
	s_andn2_b64 vcc, exec, s[10:11]
	s_cbranch_vccnz .LBB0_2009
	s_andn2_b64 vcc, exec, s[8:9]
	s_mov_b64 s[8:9], -1
	s_cbranch_vccnz .LBB0_2006
	s_nop 5
	v_sub_u32_e32 v66, s13, v150
	v_lshl_add_u32 v74, v66, 2, v152
	v_add_u32_e32 v66, 0x400, v74
	v_add_u32_e32 v68, 0x408, v74
	v_add_u32_e32 v70, 0x420, v74
	v_add_u32_e32 v72, 0x428, v74
	v_add_u32_e32 v75, 0x440, v74
	v_add_u32_e32 v76, 0x448, v74
	v_add_u32_e32 v78, 0x460, v74
	v_add_u32_e32 v80, 0x468, v74
	ds_read2_b32 v[82:83], v74 offset0:224 offset1:225
	ds_read2_b32 v[84:85], v74 offset0:226 offset1:227
	ds_read2_b32 v[86:87], v74 offset0:232 offset1:233
	ds_read2_b32 v[88:89], v74 offset0:234 offset1:235
	ds_read2_b32 v[66:67], v66 offset1:1
	ds_read2_b32 v[68:69], v68 offset1:1
	ds_read2_b32 v[70:71], v70 offset1:1
	ds_read2_b32 v[72:73], v72 offset1:1
	ds_read2_b32 v[90:91], v74 offset0:240 offset1:241
	ds_read2_b32 v[92:93], v74 offset0:242 offset1:243
	ds_read2_b32 v[94:95], v74 offset0:248 offset1:249
	ds_read2_b32 v[96:97], v74 offset0:250 offset1:251
	ds_read2_b32 v[74:75], v75 offset1:1
	ds_read2_b32 v[76:77], v76 offset1:1
	ds_read2_b32 v[78:79], v78 offset1:1
	ds_read2_b32 v[80:81], v80 offset1:1
	ds_read_b128 v[156:159], v153 offset:32768
	ds_read_b128 v[190:193], v153 offset:40960
	ds_read_b128 v[198:201], v145 offset:32768
	ds_read_b128 v[206:209], v145 offset:40960
	ds_read_b128 v[214:217], v135 offset:32768
	ds_read_b128 v[222:225], v135 offset:40960
	ds_read_b128 v[230:233], v134 offset:32768
	ds_read_b128 v[238:241], v134 offset:40960
	v_xor_b32_e32 v164, 0x80, v153
	ds_read_b128 v[164:167], v164 offset:32768
	v_xor_b32_e32 v194, 0x80, v153
	ds_read_b128 v[194:197], v194 offset:40960
	v_xor_b32_e32 v202, 0x80, v145
	ds_read_b128 v[202:205], v202 offset:32768
	v_xor_b32_e32 v210, 0x80, v145
	ds_read_b128 v[210:213], v210 offset:40960
	v_xor_b32_e32 v218, 0x80, v135
	ds_read_b128 v[218:221], v218 offset:32768
	v_xor_b32_e32 v226, 0x80, v135
	ds_read_b128 v[226:229], v226 offset:40960
	v_xor_b32_e32 v234, 0x80, v134
	ds_read_b128 v[234:237], v234 offset:32768
	v_xor_b32_e32 v242, 0x80, v134
	ds_read_b128 v[242:245], v242 offset:40960
	s_waitcnt lgkmcnt(8)
	v_mfma_f32_32x32x16_bf16 v[82:97], v[156:159], v[98:101], v[82:97]
	v_mfma_f32_32x32x16_bf16 v[66:81], v[190:193], v[98:101], v[66:81]
	v_mfma_f32_32x32x16_bf16 v[82:97], v[198:201], v[102:105], v[82:97]
	v_mfma_f32_32x32x16_bf16 v[66:81], v[206:209], v[102:105], v[66:81]
	v_mfma_f32_32x32x16_bf16 v[82:97], v[214:217], v[106:109], v[82:97]
	v_mfma_f32_32x32x16_bf16 v[66:81], v[222:225], v[106:109], v[66:81]
	v_mfma_f32_32x32x16_bf16 v[82:97], v[230:233], v[110:113], v[82:97]
	v_mfma_f32_32x32x16_bf16 v[66:81], v[238:241], v[110:113], v[66:81]
	s_waitcnt lgkmcnt(0)
	v_mfma_f32_32x32x16_bf16 v[82:97], v[164:167], v[114:117], v[82:97]
	v_mfma_f32_32x32x16_bf16 v[66:81], v[194:197], v[114:117], v[66:81]
	v_mfma_f32_32x32x16_bf16 v[82:97], v[202:205], v[118:121], v[82:97]
	v_mfma_f32_32x32x16_bf16 v[66:81], v[210:213], v[118:121], v[66:81]
	v_mfma_f32_32x32x16_bf16 v[82:97], v[218:221], v[122:125], v[82:97]
	v_mfma_f32_32x32x16_bf16 v[66:81], v[226:229], v[122:125], v[66:81]
	v_mfma_f32_32x32x16_bf16 v[82:97], v[234:237], v[126:129], v[82:97]
	v_mfma_f32_32x32x16_bf16 v[66:81], v[242:245], v[126:129], v[66:81]
	s_mov_b64 s[8:9], 0
.LBB0_2006:
	s_andn2_b64 vcc, exec, s[8:9]
	s_cbranch_vccnz .LBB0_2008
	s_nop 8
	v_or_b32_e32 v66, s13, v144
	v_sub_u32_e32 v66, v150, v66
	v_subrev_u32_e32 v67, 32, v66
	v_add_u32_e32 v70, -1, v66
	v_subrev_u32_e32 v71, 33, v66
	v_add_u32_e32 v74, -2, v66
	v_subrev_u32_e32 v75, 34, v66
	v_add_u32_e32 v78, -3, v66
	v_subrev_u32_e32 v79, 35, v66
	v_add_u32_e32 v86, -8, v66
	v_add_u32_e32 v90, -10, v66
	v_subrev_u32_e32 v91, 42, v66
	v_add_u32_e32 v94, -11, v66
	v_subrev_u32_e32 v95, 43, v66
	v_med3_i32 v68, v66, 0, v184
	v_med3_i32 v69, v67, 0, v184
	v_med3_i32 v72, v70, 0, v184
	v_med3_i32 v73, v71, 0, v184
	v_med3_i32 v76, v74, 0, v184
	v_med3_i32 v77, v75, 0, v184
	v_med3_i32 v80, v78, 0, v184
	v_med3_i32 v81, v79, 0, v184
	v_subrev_u32_e32 v87, 40, v66
	v_med3_i32 v82, v86, 0, v184
	v_add_u32_e32 v88, -9, v66
	v_subrev_u32_e32 v89, 41, v66
	v_med3_i32 v92, v90, 0, v184
	v_med3_i32 v93, v91, 0, v184
	v_med3_i32 v96, v94, 0, v184
	v_med3_i32 v97, v95, 0, v184
	v_lshl_add_u32 v68, v68, 2, s52
	v_lshl_add_u32 v69, v69, 2, s52
	v_lshl_add_u32 v72, v72, 2, s52
	v_lshl_add_u32 v73, v73, 2, s52
	v_lshl_add_u32 v76, v76, 2, s52
	v_lshl_add_u32 v77, v77, 2, s52
	v_lshl_add_u32 v80, v80, 2, s52
	v_lshl_add_u32 v81, v81, 2, s52
	v_lshl_add_u32 v82, v82, 2, s52
	v_med3_i32 v83, v87, 0, v184
	v_med3_i32 v84, v88, 0, v184
	v_med3_i32 v85, v89, 0, v184
	v_lshl_add_u32 v92, v92, 2, s52
	v_lshl_add_u32 v93, v93, 2, s52
	v_lshl_add_u32 v96, v96, 2, s52
	v_lshl_add_u32 v97, v97, 2, s52
	v_add_u32_e32 v159, -16, v66
	v_subrev_u32_e32 v164, 18, v66
	v_subrev_u32_e32 v165, 50, v66
	v_subrev_u32_e32 v180, 19, v66
	v_subrev_u32_e32 v190, 51, v66
	ds_read_b32 v68, v68
	ds_read_b32 v69, v69
	ds_read_b32 v72, v72
	ds_read_b32 v73, v73
	ds_read_b32 v76, v76
	ds_read_b32 v77, v77
	ds_read_b32 v80, v80
	ds_read_b32 v81, v81
	v_lshl_add_u32 v83, v83, 2, s52
	v_lshl_add_u32 v84, v84, 2, s52
	v_lshl_add_u32 v85, v85, 2, s52
	ds_read_b32 v154, v82
	ds_read_b32 v156, v83
	ds_read_b32 v157, v84
	ds_read_b32 v158, v85
	ds_read_b32 v92, v92
	ds_read_b32 v93, v93
	ds_read_b32 v96, v96
	ds_read_b32 v97, v97
	v_subrev_u32_e32 v160, 48, v66
	v_med3_i32 v82, v159, 0, v184
	v_subrev_u32_e32 v161, 17, v66
	v_subrev_u32_e32 v162, 49, v66
	v_med3_i32 v166, v164, 0, v184
	v_med3_i32 v167, v165, 0, v184
	v_med3_i32 v191, v180, 0, v184
	v_med3_i32 v192, v190, 0, v184
	v_lshl_add_u32 v82, v82, 2, s52
	v_med3_i32 v83, v160, 0, v184
	v_med3_i32 v84, v161, 0, v184
	v_med3_i32 v85, v162, 0, v184
	v_lshl_add_u32 v166, v166, 2, s52
	v_lshl_add_u32 v167, v167, 2, s52
	v_lshl_add_u32 v191, v191, 2, s52
	v_lshl_add_u32 v192, v192, 2, s52
	v_subrev_u32_e32 v197, 24, v66
	v_subrev_u32_e32 v201, 26, v66
	v_subrev_u32_e32 v202, 58, v66
	v_subrev_u32_e32 v205, 27, v66
	v_subrev_u32_e32 v206, 59, v66
	v_lshl_add_u32 v83, v83, 2, s52
	v_lshl_add_u32 v84, v84, 2, s52
	v_lshl_add_u32 v85, v85, 2, s52
	ds_read_b32 v193, v82
	ds_read_b32 v194, v83
	ds_read_b32 v195, v84
	ds_read_b32 v196, v85
	ds_read_b32 v166, v166
	ds_read_b32 v167, v167
	ds_read_b32 v191, v191
	ds_read_b32 v192, v192
	v_subrev_u32_e32 v198, 56, v66
	v_med3_i32 v82, v197, 0, v184
	v_subrev_u32_e32 v199, 25, v66
	v_subrev_u32_e32 v200, 57, v66
	v_med3_i32 v203, v201, 0, v184
	v_med3_i32 v204, v202, 0, v184
	v_med3_i32 v207, v205, 0, v184
	v_med3_i32 v208, v206, 0, v184
	v_lshl_add_u32 v82, v82, 2, s52
	v_med3_i32 v83, v198, 0, v184
	v_med3_i32 v84, v199, 0, v184
	v_med3_i32 v85, v200, 0, v184
	v_lshl_add_u32 v203, v203, 2, s52
	v_lshl_add_u32 v204, v204, 2, s52
	v_lshl_add_u32 v207, v207, 2, s52
	v_lshl_add_u32 v208, v208, 2, s52
	v_cmp_gt_u32_e32 vcc, s51, v66
	v_lshl_add_u32 v83, v83, 2, s52
	v_lshl_add_u32 v84, v84, 2, s52
	v_lshl_add_u32 v85, v85, 2, s52
	ds_read_b32 v209, v82
	ds_read_b32 v210, v83
	ds_read_b32 v211, v84
	ds_read_b32 v212, v85
	ds_read_b32 v203, v203
	ds_read_b32 v204, v204
	ds_read_b32 v207, v207
	ds_read_b32 v208, v208
	s_waitcnt lgkmcnt(0)
	v_cndmask_b32_e32 v82, v186, v68, vcc
	v_cmp_gt_u32_e32 vcc, s51, v67
	s_waitcnt lgkmcnt(0)
	s_nop 1
	v_cndmask_b32_e32 v66, v186, v69, vcc
	v_cmp_gt_u32_e32 vcc, s51, v70
	s_nop 1
	v_cndmask_b32_e32 v83, v186, v72, vcc
	v_cmp_gt_u32_e32 vcc, s51, v71
	s_nop 1
	v_cndmask_b32_e32 v67, v186, v73, vcc
	v_cmp_gt_u32_e32 vcc, s51, v74
	s_nop 1
	v_cndmask_b32_e32 v84, v186, v76, vcc
	v_cmp_gt_u32_e32 vcc, s51, v75
	s_nop 1
	v_cndmask_b32_e32 v68, v186, v77, vcc
	v_cmp_gt_u32_e32 vcc, s51, v78
	s_nop 1
	v_cndmask_b32_e32 v85, v186, v80, vcc
	v_cmp_gt_u32_e32 vcc, s51, v79
	s_nop 1
	v_cndmask_b32_e32 v69, v186, v81, vcc
	v_cmp_gt_u32_e32 vcc, s51, v86
	s_nop 1
	v_cndmask_b32_e32 v86, v186, v154, vcc
	v_cmp_gt_u32_e32 vcc, s51, v87
	s_nop 1
	v_cndmask_b32_e32 v70, v186, v156, vcc
	v_cmp_gt_u32_e32 vcc, s51, v88
	s_nop 1
	v_cndmask_b32_e32 v87, v186, v157, vcc
	v_cmp_gt_u32_e32 vcc, s51, v89
	s_nop 1
	v_cndmask_b32_e32 v71, v186, v158, vcc
	v_cmp_gt_u32_e32 vcc, s51, v90
	s_nop 1
	v_cndmask_b32_e32 v88, v186, v92, vcc
	v_cmp_gt_u32_e32 vcc, s51, v91
	s_nop 1
	v_cndmask_b32_e32 v72, v186, v93, vcc
	v_cmp_gt_u32_e32 vcc, s51, v94
	s_nop 1
	v_cndmask_b32_e32 v89, v186, v96, vcc
	v_cmp_gt_u32_e32 vcc, s51, v95
	s_nop 1
	v_cndmask_b32_e32 v73, v186, v97, vcc
	v_cmp_gt_u32_e32 vcc, s51, v159
	s_nop 1
	v_cndmask_b32_e32 v90, v186, v193, vcc
	v_cmp_gt_u32_e32 vcc, s51, v160
	s_nop 1
	v_cndmask_b32_e32 v74, v186, v194, vcc
	v_cmp_gt_u32_e32 vcc, s51, v161
	s_nop 1
	v_cndmask_b32_e32 v91, v186, v195, vcc
	v_cmp_gt_u32_e32 vcc, s51, v162
	s_nop 1
	v_cndmask_b32_e32 v75, v186, v196, vcc
	v_cmp_gt_u32_e32 vcc, s51, v164
	s_nop 1
	v_cndmask_b32_e32 v92, v186, v166, vcc
	v_cmp_gt_u32_e32 vcc, s51, v165
	s_nop 1
	v_cndmask_b32_e32 v76, v186, v167, vcc
	v_cmp_gt_u32_e32 vcc, s51, v180
	s_nop 1
	v_cndmask_b32_e32 v93, v186, v191, vcc
	v_cmp_gt_u32_e32 vcc, s51, v190
	s_nop 1
	v_cndmask_b32_e32 v77, v186, v192, vcc
	v_cmp_gt_u32_e32 vcc, s51, v197
	s_nop 1
	v_cndmask_b32_e32 v94, v186, v209, vcc
	v_cmp_gt_u32_e32 vcc, s51, v198
	s_nop 1
	v_cndmask_b32_e32 v78, v186, v210, vcc
	v_cmp_gt_u32_e32 vcc, s51, v199
	s_nop 1
	v_cndmask_b32_e32 v95, v186, v211, vcc
	v_cmp_gt_u32_e32 vcc, s51, v200
	s_nop 1
	v_cndmask_b32_e32 v79, v186, v212, vcc
	v_cmp_gt_u32_e32 vcc, s51, v201
	s_nop 1
	v_cndmask_b32_e32 v96, v186, v203, vcc
	v_cmp_gt_u32_e32 vcc, s51, v202
	s_nop 1
	v_cndmask_b32_e32 v80, v186, v204, vcc
	v_cmp_gt_u32_e32 vcc, s51, v205
	s_nop 1
	v_cndmask_b32_e32 v97, v186, v207, vcc
	v_cmp_gt_u32_e32 vcc, s51, v206
	s_nop 1
	v_cndmask_b32_e32 v81, v186, v208, vcc
	ds_read_b128 v[156:159], v153 offset:32768
	ds_read_b128 v[190:193], v153 offset:40960
	ds_read_b128 v[198:201], v145 offset:32768
	ds_read_b128 v[206:209], v145 offset:40960
	ds_read_b128 v[214:217], v135 offset:32768
	ds_read_b128 v[222:225], v135 offset:40960
	ds_read_b128 v[230:233], v134 offset:32768
	ds_read_b128 v[238:241], v134 offset:40960
	v_xor_b32_e32 v164, 0x80, v153
	ds_read_b128 v[164:167], v164 offset:32768
	v_xor_b32_e32 v194, 0x80, v153
	ds_read_b128 v[194:197], v194 offset:40960
	v_xor_b32_e32 v202, 0x80, v145
	ds_read_b128 v[202:205], v202 offset:32768
	v_xor_b32_e32 v210, 0x80, v145
	ds_read_b128 v[210:213], v210 offset:40960
	v_xor_b32_e32 v218, 0x80, v135
	ds_read_b128 v[218:221], v218 offset:32768
	v_xor_b32_e32 v226, 0x80, v135
	ds_read_b128 v[226:229], v226 offset:40960
	v_xor_b32_e32 v234, 0x80, v134
	ds_read_b128 v[234:237], v234 offset:32768
	v_xor_b32_e32 v242, 0x80, v134
	ds_read_b128 v[242:245], v242 offset:40960
	s_waitcnt lgkmcnt(8)
	v_mfma_f32_32x32x16_bf16 v[82:97], v[156:159], v[98:101], v[82:97]
	v_mfma_f32_32x32x16_bf16 v[66:81], v[190:193], v[98:101], v[66:81]
	v_mfma_f32_32x32x16_bf16 v[82:97], v[198:201], v[102:105], v[82:97]
	v_mfma_f32_32x32x16_bf16 v[66:81], v[206:209], v[102:105], v[66:81]
	v_mfma_f32_32x32x16_bf16 v[82:97], v[214:217], v[106:109], v[82:97]
	v_mfma_f32_32x32x16_bf16 v[66:81], v[222:225], v[106:109], v[66:81]
	v_mfma_f32_32x32x16_bf16 v[82:97], v[230:233], v[110:113], v[82:97]
	v_mfma_f32_32x32x16_bf16 v[66:81], v[238:241], v[110:113], v[66:81]
	s_waitcnt lgkmcnt(0)
	v_mfma_f32_32x32x16_bf16 v[82:97], v[164:167], v[114:117], v[82:97]
	v_mfma_f32_32x32x16_bf16 v[66:81], v[194:197], v[114:117], v[66:81]
	v_mfma_f32_32x32x16_bf16 v[82:97], v[202:205], v[118:121], v[82:97]
	v_mfma_f32_32x32x16_bf16 v[66:81], v[210:213], v[118:121], v[66:81]
	v_mfma_f32_32x32x16_bf16 v[82:97], v[218:221], v[122:125], v[82:97]
	v_mfma_f32_32x32x16_bf16 v[66:81], v[226:229], v[122:125], v[66:81]
	v_mfma_f32_32x32x16_bf16 v[82:97], v[234:237], v[126:129], v[82:97]
	v_mfma_f32_32x32x16_bf16 v[66:81], v[242:245], v[126:129], v[66:81]
